# non-temporal hint on the read-once activation loads of the pre-norm and final-norm phases and on the final output stores; on v61
# speedup vs baseline: 1.0150x; 1.0150x over previous
; __device__ __forceinline__ float rsq_f(float x) { return __builtin_amdgcn_rsqf(x); }
; __device__ __forceinline__ void phase_norm(const float* xp, const float* xs, const float* ng, const float* modl, bf16_t* hb, int gw, int NGW, int lane) {
;     ...
;         const int row0 = gw * 4, mrow = row0 / SEQ;
;         const float* sh = modl + (size_t)mrow * MODLD; const float* sc = sh + DM;
;         f32x4 gg[8], ss0[8];
; #pragma unroll
;         for (int j = 0; j < 8; ++j) { const int c4 = lane + 64 * j; gg[j] = ((const f32x4*)ng)[c4] * (1.f + ((const f32x4*)sc)[c4]); ss0[j] = ((const f32x4*)sh)[c4]; }
; #pragma unroll
;         for (int k = 0; k < 4; ++k) {
;             f32x4 v[8]; float ss = 0.f;
; #pragma unroll
;             for (int j = 0; j < 8; ++j) { v[j] = ((const f32x4*)(xp + (size_t)(row0 + k) * DM))[lane + 64 * j]; ss += (v[j].x * v[j].x + v[j].y * v[j].y) + (v[j].z * v[j].z + v[j].w * v[j].w); }
;             const float rstd = rsq_f(wave_sum2(ss, lane) * (1.f / DM) + EPS);
.LBB0_276:
	v_and_b32_e32 v128, 63, v0
	v_mov_b64_e32 v[0:1], s[6:7]
	flat_load_dwordx2 v[0:1], v[0:1] offset:56
	s_mul_hi_u32 s7, s92, 0x1800
	s_mul_i32 s6, s92, 0x1800
	s_ashr_i32 s4, s9, 6
	s_lshl_b32 s5, s8, 3
	s_lshl_b32 s38, s92, 11
	v_writelane_b32 v254, s6, 8
	s_add_i32 s4, s4, s5
	s_ashr_i32 s5, s4, 31
	v_writelane_b32 v254, s7, 9
	v_lshlrev_b32_e32 v152, 4, v128
	v_or_b32_e32 v8, 0x400, v152
	v_mov_b32_e32 v9, v153
	v_or_b32_e32 v12, 0x800, v152
	v_mov_b32_e32 v13, v153
	v_or_b32_e32 v18, 0xc00, v152
	v_mov_b32_e32 v19, v153
	v_or_b32_e32 v120, 0x1000, v152
	v_mov_b32_e32 v121, v153
	v_or_b32_e32 v116, 0x1400, v152
	v_mov_b32_e32 v117, v153
	v_or_b32_e32 v118, 0x1800, v152
	v_mov_b32_e32 v119, v153
	v_or_b32_e32 v114, 0x1c00, v152
	v_mov_b32_e32 v115, v153
	s_waitcnt vmcnt(0) lgkmcnt(0)
	v_lshl_add_u64 v[16:17], s[38:39], 2, v[0:1]
	v_lshl_add_u64 v[0:1], s[6:7], 2, v[64:65]
	s_mov_b64 s[6:7], 0x10300000
	v_lshl_add_u64 v[0:1], v[0:1], 0, s[6:7]
	s_mov_b64 s[6:7], 0x11b00000
	v_lshl_add_u64 v[78:79], v[64:65], 0, s[6:7]
	s_lshr_b32 s6, s5, 23
	s_add_i32 s6, s4, s6
	s_ashr_i32 s6, s6, 9
	v_mad_i64_i32 v[36:37], s[6:7], s6, v193, v[0:1]
	v_lshl_add_u64 v[38:39], v[36:37], 0, s[52:53]
	v_lshl_add_u64 v[4:5], v[38:39], 0, v[152:153]
	v_lshl_add_u64 v[66:67], v[16:17], 0, v[152:153]
	global_load_dwordx4 v[4:7], v[4:5], off nt
	v_lshl_add_u64 v[22:23], v[36:37], 0, v[152:153]
	global_load_dwordx4 v[0:3], v[66:67], off nt
	v_lshl_add_u64 v[8:9], v[38:39], 0, v[8:9]
	v_lshl_add_u64 v[12:13], v[38:39], 0, v[12:13]
	v_lshl_add_u64 v[18:19], v[38:39], 0, v[18:19]
	v_lshl_add_u64 v[68:69], v[16:17], 0, v[120:121]
	v_lshl_add_u64 v[70:71], v[16:17], 0, v[116:117]
	v_lshl_add_u64 v[72:73], v[16:17], 0, v[118:119]
	v_lshl_add_u64 v[74:75], v[16:17], 0, v[114:115]
	s_lshl_b32 s6, s4, 2
	s_ashr_i32 s7, s6, 31
	s_lshl_b64 s[8:9], s[6:7], 13
	v_lshl_add_u64 v[60:61], v[112:113], 0, s[8:9]
	v_lshl_add_u64 v[40:41], v[60:61], 0, v[152:153]
	s_lshl_b64 s[8:9], s[6:7], 12
	s_waitcnt vmcnt(1)
	v_pk_add_f32 v[6:7], v[6:7], 1.0 op_sel_hi:[1,0]
	v_pk_add_f32 v[4:5], v[4:5], 1.0 op_sel_hi:[1,0]
	s_waitcnt vmcnt(0)
	v_pk_mul_f32 v[80:81], v[2:3], v[6:7]
	v_pk_mul_f32 v[82:83], v[0:1], v[4:5]
	global_load_dwordx4 v[0:3], v[22:23], off nt
	global_load_dwordx4 v[4:7], v[66:67], off offset:1024 nt
	s_nop 0
	global_load_dwordx4 v[8:11], v[8:9], off nt
	s_waitcnt vmcnt(0)
	v_pk_add_f32 v[10:11], v[10:11], 1.0 op_sel_hi:[1,0]
	v_pk_add_f32 v[8:9], v[8:9], 1.0 op_sel_hi:[1,0]
	v_pk_mul_f32 v[84:85], v[6:7], v[10:11]
	v_pk_mul_f32 v[86:87], v[4:5], v[8:9]
	global_load_dwordx4 v[4:7], v[22:23], off offset:1024 nt
	global_load_dwordx4 v[8:11], v[66:67], off offset:2048 nt
	s_nop 0
	global_load_dwordx4 v[12:15], v[12:13], off nt
	s_waitcnt vmcnt(0)
	v_pk_add_f32 v[14:15], v[14:15], 1.0 op_sel_hi:[1,0]
	v_pk_add_f32 v[12:13], v[12:13], 1.0 op_sel_hi:[1,0]
	v_pk_mul_f32 v[88:89], v[10:11], v[14:15]
	v_pk_mul_f32 v[90:91], v[8:9], v[12:13]
	global_load_dwordx4 v[8:11], v[22:23], off offset:2048 nt
	global_load_dwordx4 v[12:15], v[66:67], off offset:3072 nt
	s_nop 0
	global_load_dwordx4 v[18:21], v[18:19], off nt
	s_waitcnt vmcnt(0)
	v_pk_add_f32 v[20:21], v[20:21], 1.0 op_sel_hi:[1,0]
	v_pk_add_f32 v[18:19], v[18:19], 1.0 op_sel_hi:[1,0]
	v_pk_mul_f32 v[96:97], v[14:15], v[20:21]
	v_pk_mul_f32 v[98:99], v[12:13], v[18:19]
	global_load_dwordx4 v[12:15], v[22:23], off offset:3072 nt
	v_lshl_add_u64 v[22:23], v[38:39], 0, v[120:121]
	global_load_dwordx4 v[22:25], v[22:23], off nt
	s_waitcnt vmcnt(0)
	v_pk_add_f32 v[22:23], v[22:23], 1.0 op_sel_hi:[1,0]
	global_load_dwordx4 v[18:21], v[68:69], off nt
	v_pk_add_f32 v[24:25], v[24:25], 1.0 op_sel_hi:[1,0]
	s_waitcnt vmcnt(0)
	v_pk_mul_f32 v[110:111], v[18:19], v[22:23]
	v_lshl_add_u64 v[18:19], v[36:37], 0, v[120:121]
	v_lshl_add_u64 v[22:23], v[38:39], 0, v[116:117]
	v_pk_mul_f32 v[108:109], v[20:21], v[24:25]
	global_load_dwordx4 v[28:31], v[18:19], off nt
	s_nop 0
	global_load_dwordx4 v[22:25], v[22:23], off nt
	s_waitcnt vmcnt(0)
	v_pk_add_f32 v[22:23], v[22:23], 1.0 op_sel_hi:[1,0]
	global_load_dwordx4 v[18:21], v[70:71], off nt
	v_pk_add_f32 v[24:25], v[24:25], 1.0 op_sel_hi:[1,0]
	s_waitcnt vmcnt(0)
	v_pk_mul_f32 v[106:107], v[18:19], v[22:23]
	v_lshl_add_u64 v[18:19], v[36:37], 0, v[116:117]
	v_lshl_add_u64 v[22:23], v[38:39], 0, v[118:119]
	v_pk_mul_f32 v[104:105], v[20:21], v[24:25]
	global_load_dwordx4 v[24:27], v[18:19], off nt
	global_load_dwordx4 v[32:35], v[22:23], off nt
	s_waitcnt vmcnt(0)
	v_pk_add_f32 v[32:33], v[32:33], 1.0 op_sel_hi:[1,0]
	global_load_dwordx4 v[18:21], v[72:73], off nt
	v_pk_add_f32 v[22:23], v[34:35], 1.0 op_sel_hi:[1,0]
	s_waitcnt vmcnt(0)
	v_pk_mul_f32 v[102:103], v[18:19], v[32:33]
	v_lshl_add_u64 v[18:19], v[36:37], 0, v[118:119]
	v_lshl_add_u64 v[32:33], v[38:39], 0, v[114:115]
	v_pk_mul_f32 v[100:101], v[20:21], v[22:23]
	global_load_dwordx4 v[20:23], v[18:19], off nt
	s_nop 0
	global_load_dwordx4 v[32:35], v[32:33], off nt
	s_waitcnt vmcnt(0)
	v_pk_add_f32 v[32:33], v[32:33], 1.0 op_sel_hi:[1,0]
	global_load_dwordx4 v[16:19], v[74:75], off nt
	v_pk_add_f32 v[34:35], v[34:35], 1.0 op_sel_hi:[1,0]
	s_waitcnt vmcnt(0)
	v_pk_mul_f32 v[94:95], v[16:17], v[32:33]
	v_lshl_add_u64 v[16:17], v[36:37], 0, v[114:115]
	v_lshlrev_b32_e32 v32, 2, v128
	v_pk_mul_f32 v[92:93], v[18:19], v[34:35]
	global_load_dwordx4 v[16:19], v[16:17], off nt
	v_xor_b32_e32 v126, 64, v32
	v_xor_b32_e32 v127, 0x80, v32
	global_load_dwordx4 v[36:39], v[40:41], off nt
	global_load_dwordx4 v[32:35], v[40:41], off offset:1024 nt
	s_waitcnt vmcnt(1)
	v_mov_b32_e32 v44, v37
	s_waitcnt vmcnt(0)
; __device__ __forceinline__ unsigned pk2(float lo, float hi) { return pg8::cvt_pk_bf16(lo, hi); }
; __device__ __forceinline__ float rsq_f(float x) { return __builtin_amdgcn_rsqf(x); }
; __device__ __forceinline__ void phase_norm(const float* xp, const float* xs, const float* ng, const float* modl, bf16_t* hb, int gw, int NGW, int lane) {
;     ...
;             f32x4 v[8]; float ss = 0.f;
; #pragma unroll
;             for (int j = 0; j < 8; ++j) { v[j] = ((const f32x4*)(xp + (size_t)(row0 + k) * DM))[lane + 64 * j]; ss += (v[j].x * v[j].x + v[j].y * v[j].y) + (v[j].z * v[j].z + v[j].w * v[j].w); }
;             const float rstd = rsq_f(wave_sum2(ss, lane) * (1.f / DM) + EPS);
; #pragma unroll
;             for (int j = 0; j < 8; ++j) { const int c4 = lane + 64 * j; const f32x4 h = v[j] * rstd * gg[j] + ss0[j]; u32x2 o; o.x = pk2(h.x, h.y); o.y = pk2(h.z, h.w); *(u32x2*)(hb + (size_t)(row0 + k) * DM + c4 * 4) = o; }
;         }
	v_mov_b32_e32 v45, v33
	v_mov_b32_e32 v42, v36
	v_mov_b32_e32 v43, v32
	v_pk_mul_f32 v[44:45], v[44:45], v[44:45]
	v_mov_b32_e32 v46, v39
	v_mov_b32_e32 v47, v35
	v_pk_fma_f32 v[42:43], v[42:43], v[42:43], v[44:45]
	v_mov_b32_e32 v44, v38
	v_mov_b32_e32 v45, v34
	v_pk_mul_f32 v[46:47], v[46:47], v[46:47]
	s_nop 0
	v_pk_fma_f32 v[44:45], v[44:45], v[44:45], v[46:47]
	s_nop 0
	v_pk_add_f32 v[52:53], v[42:43], v[44:45]
	global_load_dwordx4 v[44:47], v[40:41], off offset:2048 nt
	v_pk_add_f32 v[52:53], v[52:53], v[52:53] op_sel:[0,1] op_sel_hi:[1,0]
	s_waitcnt vmcnt(0)
	v_pk_mul_f32 v[42:43], v[46:47], v[46:47]
	v_pk_mul_f32 v[48:49], v[44:45], v[44:45]
	s_nop 0
	v_pk_mov_b32 v[50:51], v[48:49], v[42:43] op_sel:[1,0]
	v_mov_b32_e32 v49, v43
	v_pk_add_f32 v[54:55], v[50:51], v[48:49]
	v_lshl_add_u64 v[48:49], v[60:61], 0, v[120:121]
	global_load_dwordx4 v[40:43], v[40:41], off offset:3072 nt
	v_pk_add_f32 v[54:55], v[54:55], v[54:55] op_sel:[0,1] op_sel_hi:[1,0]
	global_load_dwordx4 v[48:51], v[48:49], off nt
	s_waitcnt vmcnt(0)
	v_mul_f32_e32 v56, v48, v48
	v_mul_f32_e32 v57, v49, v49
	v_mov_b32_e32 v53, v56
	v_mov_b32_e32 v55, v57
	v_pk_add_f32 v[52:53], v[52:53], v[54:55]
	v_mul_f32_e32 v54, v41, v41
	v_mul_f32_e32 v56, v43, v43
	v_mul_f32_e32 v58, v50, v50
	v_mul_f32_e32 v59, v51, v51
	v_pk_fma_f32 v[54:55], v[40:41], v[40:41], v[54:55] op_sel_hi:[1,1,0]
	v_pk_fma_f32 v[56:57], v[42:43], v[42:43], v[56:57] op_sel_hi:[1,1,0]
	v_mov_b32_e32 v55, v58
	v_mov_b32_e32 v57, v59
	v_pk_add_f32 v[54:55], v[54:55], v[56:57]
	s_nop 0
	v_pk_add_f32 v[122:123], v[52:53], v[54:55]
	v_lshl_add_u64 v[52:53], v[60:61], 0, v[116:117]
	global_load_dwordx4 v[56:59], v[52:53], off nt
	v_pk_add_f32 v[122:123], v[122:123], v[122:123] op_sel:[0,1] op_sel_hi:[1,0]
	s_waitcnt vmcnt(0)
	v_pk_mul_f32 v[52:53], v[58:59], v[58:59]
	v_pk_mul_f32 v[54:55], v[56:57], v[56:57]
	s_nop 0
	v_pk_mov_b32 v[62:63], v[54:55], v[52:53] op_sel:[1,0]
	v_mov_b32_e32 v55, v53
	v_lshl_add_u64 v[52:53], v[60:61], 0, v[118:119]
	v_lshl_add_u64 v[60:61], v[60:61], 0, v[114:115]
	v_pk_add_f32 v[124:125], v[62:63], v[54:55]
	global_load_dwordx4 v[52:55], v[52:53], off nt
	v_pk_add_f32 v[124:125], v[124:125], v[124:125] op_sel:[0,1] op_sel_hi:[1,0]
	global_load_dwordx4 v[60:63], v[60:61], off nt
	s_waitcnt vmcnt(0)
	v_mul_f32_e32 v129, v60, v60
	v_mul_f32_e32 v130, v61, v61
	v_mov_b32_e32 v123, v129
	v_mov_b32_e32 v125, v130
	v_pk_add_f32 v[122:123], v[122:123], v[124:125]
	v_mul_f32_e32 v124, v53, v53
	v_mul_f32_e32 v131, v62, v62
	v_pk_fma_f32 v[124:125], v[52:53], v[52:53], v[124:125] op_sel_hi:[1,1,0]
	v_mul_f32_e32 v130, v55, v55
	v_mul_f32_e32 v132, v63, v63
	v_mov_b32_e32 v125, v131
	v_pk_fma_f32 v[130:131], v[54:55], v[54:55], v[130:131] op_sel_hi:[1,1,0]
	s_nop 0
	v_mov_b32_e32 v131, v132
	v_pk_add_f32 v[124:125], v[124:125], v[130:131]
	v_lshl_add_u64 v[130:131], v[78:79], 0, s[8:9]
	v_pk_add_f32 v[122:123], v[122:123], v[124:125]
	s_or_b32 s8, s6, 1
	v_add_f32_e32 v122, v122, v123
	s_ashr_i32 s9, s8, 31
	s_lshl_b64 s[10:11], s[8:9], 13
	v_add_f32_dpp v122, v122, v122 quad_perm:[1,0,3,2] row_mask:0xf bank_mask:0xf bound_ctrl:1
	s_lshl_b64 s[8:9], s[8:9], 12
	s_nop 0
	v_add_f32_dpp v122, v122, v122 quad_perm:[2,3,0,1] row_mask:0xf bank_mask:0xf bound_ctrl:1
	s_nop 1
	v_add_f32_dpp v122, v122, v122 row_half_mirror row_mask:0xf bank_mask:0xf bound_ctrl:1
	s_nop 1
	v_add_f32_dpp v122, v122, v122 row_mirror row_mask:0xf bank_mask:0xf bound_ctrl:1
	ds_bpermute_b32 v123, v126, v122
	s_waitcnt lgkmcnt(0)
	v_add_f32_e32 v122, v122, v123
	ds_bpermute_b32 v123, v127, v122
	s_waitcnt lgkmcnt(0)
	v_add_f32_e32 v122, v122, v123
	v_fmamk_f32 v122, v122, 0x3a000000, v194
	v_rsq_f32_e32 v124, v122
	v_lshlrev_b32_e32 v122, 3, v128
	v_mov_b32_e32 v123, v153
	v_pk_mul_f32 v[36:37], v[36:37], v[124:125] op_sel_hi:[1,0]
	v_pk_mul_f32 v[38:39], v[38:39], v[124:125] op_sel_hi:[1,0]
	v_pk_mul_f32 v[32:33], v[32:33], v[124:125] op_sel_hi:[1,0]
	v_pk_fma_f32 v[38:39], v[80:81], v[38:39], v[2:3]
	v_pk_fma_f32 v[36:37], v[82:83], v[36:37], v[0:1]
	v_pk_mul_f32 v[34:35], v[34:35], v[124:125] op_sel_hi:[1,0]
	v_pk_fma_f32 v[32:33], v[86:87], v[32:33], v[4:5]
	v_cvt_pk_bf16_f32 v36, v36, v37
	v_cvt_pk_bf16_f32 v37, v38, v39
	v_lshl_add_u64 v[38:39], v[130:131], 0, v[122:123]
	v_pk_fma_f32 v[34:35], v[84:85], v[34:35], v[6:7]
	v_cvt_pk_bf16_f32 v32, v32, v33
	global_store_dwordx2 v[38:39], v[36:37], off
	v_cvt_pk_bf16_f32 v33, v34, v35
	global_store_dwordx2 v[38:39], v[32:33], off offset:512
	v_pk_mul_f32 v[32:33], v[44:45], v[124:125] op_sel_hi:[1,0]
	v_pk_mul_f32 v[34:35], v[46:47], v[124:125] op_sel_hi:[1,0]
	v_pk_fma_f32 v[32:33], v[90:91], v[32:33], v[8:9]
	v_pk_fma_f32 v[34:35], v[88:89], v[34:35], v[10:11]
	v_cvt_pk_bf16_f32 v32, v32, v33
	s_nop 0
	v_cvt_pk_bf16_f32 v33, v34, v35
	global_store_dwordx2 v[38:39], v[32:33], off offset:1024
	v_pk_mul_f32 v[32:33], v[40:41], v[124:125] op_sel_hi:[1,0]
	v_pk_mul_f32 v[34:35], v[42:43], v[124:125] op_sel_hi:[1,0]
	v_pk_fma_f32 v[32:33], v[98:99], v[32:33], v[12:13]
	v_pk_fma_f32 v[34:35], v[96:97], v[34:35], v[14:15]
	v_cvt_pk_bf16_f32 v32, v32, v33
	s_nop 0
	v_cvt_pk_bf16_f32 v33, v34, v35
	global_store_dwordx2 v[38:39], v[32:33], off offset:1536
	v_pk_mul_f32 v[32:33], v[48:49], v[124:125] op_sel_hi:[1,0]
	v_pk_mul_f32 v[34:35], v[50:51], v[124:125] op_sel_hi:[1,0]
	v_pk_fma_f32 v[32:33], v[110:111], v[32:33], v[28:29]
	v_pk_fma_f32 v[34:35], v[108:109], v[34:35], v[30:31]
	v_cvt_pk_bf16_f32 v32, v32, v33
	s_nop 0
	v_cvt_pk_bf16_f32 v33, v34, v35
	global_store_dwordx2 v[38:39], v[32:33], off offset:2048
	v_pk_mul_f32 v[32:33], v[56:57], v[124:125] op_sel_hi:[1,0]
	v_pk_mul_f32 v[34:35], v[58:59], v[124:125] op_sel_hi:[1,0]
	v_pk_fma_f32 v[32:33], v[106:107], v[32:33], v[24:25]
	v_pk_fma_f32 v[34:35], v[104:105], v[34:35], v[26:27]
	v_cvt_pk_bf16_f32 v32, v32, v33
	s_nop 0
	v_cvt_pk_bf16_f32 v33, v34, v35
	global_store_dwordx2 v[38:39], v[32:33], off offset:2560
	v_pk_mul_f32 v[32:33], v[52:53], v[124:125] op_sel_hi:[1,0]
	v_pk_mul_f32 v[34:35], v[54:55], v[124:125] op_sel_hi:[1,0]
	v_pk_fma_f32 v[32:33], v[102:103], v[32:33], v[20:21]
	v_pk_fma_f32 v[34:35], v[100:101], v[34:35], v[22:23]
	v_cvt_pk_bf16_f32 v32, v32, v33
	s_nop 0
	v_cvt_pk_bf16_f32 v33, v34, v35
	global_store_dwordx2 v[38:39], v[32:33], off offset:3072
	v_pk_mul_f32 v[32:33], v[60:61], v[124:125] op_sel_hi:[1,0]
	v_pk_mul_f32 v[34:35], v[62:63], v[124:125] op_sel_hi:[1,0]
	v_pk_fma_f32 v[32:33], v[94:95], v[32:33], v[16:17]
	v_lshl_add_u64 v[60:61], v[112:113], 0, s[10:11]
	v_pk_fma_f32 v[34:35], v[92:93], v[34:35], v[18:19]
	v_cvt_pk_bf16_f32 v32, v32, v33
	v_lshl_add_u64 v[40:41], v[60:61], 0, v[152:153]
	v_cvt_pk_bf16_f32 v33, v34, v35
	global_store_dwordx2 v[38:39], v[32:33], off offset:3584
	global_load_dwordx4 v[36:39], v[40:41], off nt
	s_nop 0
	global_load_dwordx4 v[32:35], v[40:41], off offset:1024 nt
	s_waitcnt vmcnt(1)
; __device__ __forceinline__ unsigned pk2(float lo, float hi) { return pg8::cvt_pk_bf16(lo, hi); }
; __device__ __forceinline__ float rsq_f(float x) { return __builtin_amdgcn_rsqf(x); }
; __device__ __forceinline__ void phase_norm(const float* xp, const float* xs, const float* ng, const float* modl, bf16_t* hb, int gw, int NGW, int lane) {
;     ...
;         for (int k = 0; k < 4; ++k) {
;             f32x4 v[8]; float ss = 0.f;
; #pragma unroll
;             for (int j = 0; j < 8; ++j) { v[j] = ((const f32x4*)(xp + (size_t)(row0 + k) * DM))[lane + 64 * j]; ss += (v[j].x * v[j].x + v[j].y * v[j].y) + (v[j].z * v[j].z + v[j].w * v[j].w); }
;             const float rstd = rsq_f(wave_sum2(ss, lane) * (1.f / DM) + EPS);
; #pragma unroll
;             for (int j = 0; j < 8; ++j) { const int c4 = lane + 64 * j; const f32x4 h = v[j] * rstd * gg[j] + ss0[j]; u32x2 o; o.x = pk2(h.x, h.y); o.y = pk2(h.z, h.w); *(u32x2*)(hb + (size_t)(row0 + k) * DM + c4 * 4) = o; }
;         }
	v_mov_b32_e32 v44, v37
	s_waitcnt vmcnt(0)
	v_mov_b32_e32 v45, v33
	v_mov_b32_e32 v42, v36
	v_mov_b32_e32 v43, v32
	v_pk_mul_f32 v[44:45], v[44:45], v[44:45]
	v_mov_b32_e32 v46, v39
	v_mov_b32_e32 v47, v35
	v_pk_fma_f32 v[42:43], v[42:43], v[42:43], v[44:45]
	v_mov_b32_e32 v44, v38
	v_mov_b32_e32 v45, v34
	v_pk_mul_f32 v[46:47], v[46:47], v[46:47]
	s_nop 0
	v_pk_fma_f32 v[44:45], v[44:45], v[44:45], v[46:47]
	s_nop 0
	v_pk_add_f32 v[52:53], v[42:43], v[44:45]
	global_load_dwordx4 v[44:47], v[40:41], off offset:2048 nt
	v_pk_add_f32 v[52:53], v[52:53], v[52:53] op_sel:[0,1] op_sel_hi:[1,0]
	s_waitcnt vmcnt(0)
	v_pk_mul_f32 v[42:43], v[46:47], v[46:47]
	v_pk_mul_f32 v[48:49], v[44:45], v[44:45]
	s_nop 0
	v_pk_mov_b32 v[50:51], v[48:49], v[42:43] op_sel:[1,0]
	v_mov_b32_e32 v49, v43
	v_pk_add_f32 v[54:55], v[50:51], v[48:49]
	v_lshl_add_u64 v[48:49], v[60:61], 0, v[120:121]
	global_load_dwordx4 v[40:43], v[40:41], off offset:3072 nt
	v_pk_add_f32 v[54:55], v[54:55], v[54:55] op_sel:[0,1] op_sel_hi:[1,0]
	global_load_dwordx4 v[48:51], v[48:49], off nt
	s_waitcnt vmcnt(0)
	v_mul_f32_e32 v56, v48, v48
	v_mul_f32_e32 v57, v49, v49
	v_mov_b32_e32 v53, v56
	v_mov_b32_e32 v55, v57
	v_pk_add_f32 v[52:53], v[52:53], v[54:55]
	v_mul_f32_e32 v54, v41, v41
	v_mul_f32_e32 v56, v43, v43
	v_mul_f32_e32 v58, v50, v50
	v_mul_f32_e32 v59, v51, v51
	v_pk_fma_f32 v[54:55], v[40:41], v[40:41], v[54:55] op_sel_hi:[1,1,0]
	v_pk_fma_f32 v[56:57], v[42:43], v[42:43], v[56:57] op_sel_hi:[1,1,0]
	v_mov_b32_e32 v55, v58
	v_mov_b32_e32 v57, v59
	v_pk_add_f32 v[54:55], v[54:55], v[56:57]
	s_nop 0
	v_pk_add_f32 v[124:125], v[52:53], v[54:55]
	v_lshl_add_u64 v[52:53], v[60:61], 0, v[116:117]
	global_load_dwordx4 v[56:59], v[52:53], off nt
	v_pk_add_f32 v[124:125], v[124:125], v[124:125] op_sel:[0,1] op_sel_hi:[1,0]
	s_waitcnt vmcnt(0)
	v_pk_mul_f32 v[52:53], v[58:59], v[58:59]
	v_pk_mul_f32 v[54:55], v[56:57], v[56:57]
	s_nop 0
	v_pk_mov_b32 v[62:63], v[54:55], v[52:53] op_sel:[1,0]
	v_mov_b32_e32 v55, v53
	v_lshl_add_u64 v[52:53], v[60:61], 0, v[118:119]
	v_lshl_add_u64 v[60:61], v[60:61], 0, v[114:115]
	v_pk_add_f32 v[130:131], v[62:63], v[54:55]
	global_load_dwordx4 v[52:55], v[52:53], off nt
	v_pk_add_f32 v[130:131], v[130:131], v[130:131] op_sel:[0,1] op_sel_hi:[1,0]
	global_load_dwordx4 v[60:63], v[60:61], off nt
	s_waitcnt vmcnt(0)
	v_mul_f32_e32 v129, v60, v60
	v_mul_f32_e32 v132, v61, v61
	v_mov_b32_e32 v125, v129
	v_mov_b32_e32 v131, v132
	v_pk_add_f32 v[124:125], v[124:125], v[130:131]
	v_mul_f32_e32 v130, v53, v53
	v_mul_f32_e32 v133, v62, v62
	v_pk_fma_f32 v[130:131], v[52:53], v[52:53], v[130:131] op_sel_hi:[1,1,0]
	v_mul_f32_e32 v132, v55, v55
	v_mul_f32_e32 v134, v63, v63
	v_mov_b32_e32 v131, v133
	v_pk_fma_f32 v[132:133], v[54:55], v[54:55], v[132:133] op_sel_hi:[1,1,0]
	s_nop 0
	v_mov_b32_e32 v133, v134
	v_pk_add_f32 v[130:131], v[130:131], v[132:133]
	s_nop 0
	v_pk_add_f32 v[124:125], v[124:125], v[130:131]
	v_lshl_add_u64 v[130:131], v[78:79], 0, s[8:9]
	v_add_f32_e32 v124, v124, v125
	s_or_b32 s8, s6, 2
	s_ashr_i32 s9, s8, 31
	v_add_f32_dpp v124, v124, v124 quad_perm:[1,0,3,2] row_mask:0xf bank_mask:0xf bound_ctrl:1
	s_lshl_b64 s[10:11], s[8:9], 13
	s_lshl_b64 s[8:9], s[8:9], 12
	v_add_f32_dpp v124, v124, v124 quad_perm:[2,3,0,1] row_mask:0xf bank_mask:0xf bound_ctrl:1
	s_or_b32 s6, s6, 3
	s_ashr_i32 s7, s6, 31
	v_add_f32_dpp v124, v124, v124 row_half_mirror row_mask:0xf bank_mask:0xf bound_ctrl:1
	s_nop 1
	v_add_f32_dpp v124, v124, v124 row_mirror row_mask:0xf bank_mask:0xf bound_ctrl:1
	ds_bpermute_b32 v125, v126, v124
	s_waitcnt lgkmcnt(0)
	v_add_f32_e32 v124, v124, v125
	ds_bpermute_b32 v125, v127, v124
	s_waitcnt lgkmcnt(0)
	v_add_f32_e32 v124, v124, v125
	v_fmamk_f32 v124, v124, 0x3a000000, v194
	v_rsq_f32_e32 v124, v124
	s_nop 0
	v_pk_mul_f32 v[36:37], v[36:37], v[124:125] op_sel_hi:[1,0]
	v_pk_mul_f32 v[38:39], v[38:39], v[124:125] op_sel_hi:[1,0]
	v_pk_mul_f32 v[32:33], v[32:33], v[124:125] op_sel_hi:[1,0]
	v_pk_fma_f32 v[38:39], v[80:81], v[38:39], v[2:3]
	v_pk_fma_f32 v[36:37], v[82:83], v[36:37], v[0:1]
	v_pk_mul_f32 v[34:35], v[34:35], v[124:125] op_sel_hi:[1,0]
	v_pk_fma_f32 v[32:33], v[86:87], v[32:33], v[4:5]
	v_cvt_pk_bf16_f32 v36, v36, v37
	v_cvt_pk_bf16_f32 v37, v38, v39
	v_lshl_add_u64 v[38:39], v[130:131], 0, v[122:123]
	v_pk_fma_f32 v[34:35], v[84:85], v[34:35], v[6:7]
	v_cvt_pk_bf16_f32 v32, v32, v33
	global_store_dwordx2 v[38:39], v[36:37], off
	v_cvt_pk_bf16_f32 v33, v34, v35
	global_store_dwordx2 v[38:39], v[32:33], off offset:512
	v_pk_mul_f32 v[32:33], v[44:45], v[124:125] op_sel_hi:[1,0]
	v_pk_mul_f32 v[34:35], v[46:47], v[124:125] op_sel_hi:[1,0]
	v_pk_fma_f32 v[32:33], v[90:91], v[32:33], v[8:9]
	v_pk_fma_f32 v[34:35], v[88:89], v[34:35], v[10:11]
	v_cvt_pk_bf16_f32 v32, v32, v33
	s_nop 0
	v_cvt_pk_bf16_f32 v33, v34, v35
	global_store_dwordx2 v[38:39], v[32:33], off offset:1024
	v_pk_mul_f32 v[32:33], v[40:41], v[124:125] op_sel_hi:[1,0]
	v_pk_mul_f32 v[34:35], v[42:43], v[124:125] op_sel_hi:[1,0]
	v_pk_fma_f32 v[32:33], v[98:99], v[32:33], v[12:13]
	v_pk_fma_f32 v[34:35], v[96:97], v[34:35], v[14:15]
	v_cvt_pk_bf16_f32 v32, v32, v33
	s_nop 0
	v_cvt_pk_bf16_f32 v33, v34, v35
	global_store_dwordx2 v[38:39], v[32:33], off offset:1536
	v_pk_mul_f32 v[32:33], v[48:49], v[124:125] op_sel_hi:[1,0]
	v_pk_mul_f32 v[34:35], v[50:51], v[124:125] op_sel_hi:[1,0]
	v_pk_fma_f32 v[32:33], v[110:111], v[32:33], v[28:29]
	v_pk_fma_f32 v[34:35], v[108:109], v[34:35], v[30:31]
	v_cvt_pk_bf16_f32 v32, v32, v33
	s_nop 0
	v_cvt_pk_bf16_f32 v33, v34, v35
	global_store_dwordx2 v[38:39], v[32:33], off offset:2048
	v_pk_mul_f32 v[32:33], v[56:57], v[124:125] op_sel_hi:[1,0]
	v_pk_mul_f32 v[34:35], v[58:59], v[124:125] op_sel_hi:[1,0]
	v_pk_fma_f32 v[32:33], v[106:107], v[32:33], v[24:25]
	v_pk_fma_f32 v[34:35], v[104:105], v[34:35], v[26:27]
	v_cvt_pk_bf16_f32 v32, v32, v33
	s_nop 0
	v_cvt_pk_bf16_f32 v33, v34, v35
	global_store_dwordx2 v[38:39], v[32:33], off offset:2560
	v_pk_mul_f32 v[32:33], v[52:53], v[124:125] op_sel_hi:[1,0]
	v_pk_mul_f32 v[34:35], v[54:55], v[124:125] op_sel_hi:[1,0]
	v_pk_fma_f32 v[32:33], v[102:103], v[32:33], v[20:21]
	v_pk_fma_f32 v[34:35], v[100:101], v[34:35], v[22:23]
	v_cvt_pk_bf16_f32 v32, v32, v33
	s_nop 0
	v_cvt_pk_bf16_f32 v33, v34, v35
	global_store_dwordx2 v[38:39], v[32:33], off offset:3072
	v_pk_mul_f32 v[32:33], v[60:61], v[124:125] op_sel_hi:[1,0]
	v_pk_mul_f32 v[34:35], v[62:63], v[124:125] op_sel_hi:[1,0]
	v_pk_fma_f32 v[32:33], v[94:95], v[32:33], v[16:17]
	v_lshl_add_u64 v[60:61], v[112:113], 0, s[10:11]
	v_pk_fma_f32 v[34:35], v[92:93], v[34:35], v[18:19]
	v_cvt_pk_bf16_f32 v32, v32, v33
	v_lshl_add_u64 v[40:41], v[60:61], 0, v[152:153]
	v_cvt_pk_bf16_f32 v33, v34, v35
	global_store_dwordx2 v[38:39], v[32:33], off offset:3584
	global_load_dwordx4 v[36:39], v[40:41], off nt
	s_nop 0
	global_load_dwordx4 v[32:35], v[40:41], off offset:1024 nt
	s_waitcnt vmcnt(1)
; __device__ __forceinline__ unsigned pk2(float lo, float hi) { return pg8::cvt_pk_bf16(lo, hi); }
; __device__ __forceinline__ float rsq_f(float x) { return __builtin_amdgcn_rsqf(x); }
; __device__ __forceinline__ void phase_norm(const float* xp, const float* xs, const float* ng, const float* modl, bf16_t* hb, int gw, int NGW, int lane) {
;     ...
;         for (int k = 0; k < 4; ++k) {
;             f32x4 v[8]; float ss = 0.f;
; #pragma unroll
;             for (int j = 0; j < 8; ++j) { v[j] = ((const f32x4*)(xp + (size_t)(row0 + k) * DM))[lane + 64 * j]; ss += (v[j].x * v[j].x + v[j].y * v[j].y) + (v[j].z * v[j].z + v[j].w * v[j].w); }
;             const float rstd = rsq_f(wave_sum2(ss, lane) * (1.f / DM) + EPS);
; #pragma unroll
;             for (int j = 0; j < 8; ++j) { const int c4 = lane + 64 * j; const f32x4 h = v[j] * rstd * gg[j] + ss0[j]; u32x2 o; o.x = pk2(h.x, h.y); o.y = pk2(h.z, h.w); *(u32x2*)(hb + (size_t)(row0 + k) * DM + c4 * 4) = o; }
;         }
	v_mov_b32_e32 v44, v37
	s_waitcnt vmcnt(0)
	v_mov_b32_e32 v45, v33
	v_mov_b32_e32 v42, v36
	v_mov_b32_e32 v43, v32
	v_pk_mul_f32 v[44:45], v[44:45], v[44:45]
	v_mov_b32_e32 v46, v39
	v_mov_b32_e32 v47, v35
	v_pk_fma_f32 v[42:43], v[42:43], v[42:43], v[44:45]
	v_mov_b32_e32 v44, v38
	v_mov_b32_e32 v45, v34
	v_pk_mul_f32 v[46:47], v[46:47], v[46:47]
	s_nop 0
	v_pk_fma_f32 v[44:45], v[44:45], v[44:45], v[46:47]
	s_nop 0
	v_pk_add_f32 v[52:53], v[42:43], v[44:45]
	global_load_dwordx4 v[44:47], v[40:41], off offset:2048 nt
	v_pk_add_f32 v[52:53], v[52:53], v[52:53] op_sel:[0,1] op_sel_hi:[1,0]
	s_waitcnt vmcnt(0)
	v_pk_mul_f32 v[42:43], v[46:47], v[46:47]
	v_pk_mul_f32 v[48:49], v[44:45], v[44:45]
	s_nop 0
	v_pk_mov_b32 v[50:51], v[48:49], v[42:43] op_sel:[1,0]
	v_mov_b32_e32 v49, v43
	v_pk_add_f32 v[54:55], v[50:51], v[48:49]
	v_lshl_add_u64 v[48:49], v[60:61], 0, v[120:121]
	global_load_dwordx4 v[40:43], v[40:41], off offset:3072 nt
	v_pk_add_f32 v[54:55], v[54:55], v[54:55] op_sel:[0,1] op_sel_hi:[1,0]
	global_load_dwordx4 v[48:51], v[48:49], off nt
	s_waitcnt vmcnt(0)
	v_mul_f32_e32 v56, v48, v48
	v_mul_f32_e32 v57, v49, v49
	v_mov_b32_e32 v53, v56
	v_mov_b32_e32 v55, v57
	v_pk_add_f32 v[52:53], v[52:53], v[54:55]
	v_mul_f32_e32 v54, v41, v41
	v_mul_f32_e32 v56, v43, v43
	v_mul_f32_e32 v58, v50, v50
	v_mul_f32_e32 v59, v51, v51
	v_pk_fma_f32 v[54:55], v[40:41], v[40:41], v[54:55] op_sel_hi:[1,1,0]
	v_pk_fma_f32 v[56:57], v[42:43], v[42:43], v[56:57] op_sel_hi:[1,1,0]
	v_mov_b32_e32 v55, v58
	v_mov_b32_e32 v57, v59
	v_pk_add_f32 v[54:55], v[54:55], v[56:57]
	s_nop 0
	v_pk_add_f32 v[124:125], v[52:53], v[54:55]
	v_lshl_add_u64 v[52:53], v[60:61], 0, v[116:117]
	global_load_dwordx4 v[56:59], v[52:53], off nt
	v_pk_add_f32 v[124:125], v[124:125], v[124:125] op_sel:[0,1] op_sel_hi:[1,0]
	s_waitcnt vmcnt(0)
	v_pk_mul_f32 v[52:53], v[58:59], v[58:59]
	v_pk_mul_f32 v[54:55], v[56:57], v[56:57]
	s_nop 0
	v_pk_mov_b32 v[62:63], v[54:55], v[52:53] op_sel:[1,0]
	v_mov_b32_e32 v55, v53
	v_lshl_add_u64 v[52:53], v[60:61], 0, v[118:119]
	v_lshl_add_u64 v[60:61], v[60:61], 0, v[114:115]
	v_pk_add_f32 v[130:131], v[62:63], v[54:55]
	global_load_dwordx4 v[52:55], v[52:53], off nt
	v_pk_add_f32 v[130:131], v[130:131], v[130:131] op_sel:[0,1] op_sel_hi:[1,0]
	global_load_dwordx4 v[60:63], v[60:61], off nt
	s_waitcnt vmcnt(0)
	v_mul_f32_e32 v129, v60, v60
	v_mul_f32_e32 v132, v61, v61
	v_mov_b32_e32 v125, v129
	v_mov_b32_e32 v131, v132
	v_pk_add_f32 v[124:125], v[124:125], v[130:131]
	v_mul_f32_e32 v130, v53, v53
	v_mul_f32_e32 v133, v62, v62
	v_pk_fma_f32 v[130:131], v[52:53], v[52:53], v[130:131] op_sel_hi:[1,1,0]
	v_mul_f32_e32 v132, v55, v55
	v_mul_f32_e32 v134, v63, v63
	v_mov_b32_e32 v131, v133
	v_pk_fma_f32 v[132:133], v[54:55], v[54:55], v[132:133] op_sel_hi:[1,1,0]
	s_nop 0
	v_mov_b32_e32 v133, v134
	v_pk_add_f32 v[130:131], v[130:131], v[132:133]
	s_nop 0
	v_pk_add_f32 v[124:125], v[124:125], v[130:131]
	v_lshl_add_u64 v[130:131], v[78:79], 0, s[8:9]
	v_add_f32_e32 v124, v124, v125
	s_lshl_b64 s[8:9], s[6:7], 13
	s_lshl_b64 s[6:7], s[6:7], 12
	v_add_f32_dpp v124, v124, v124 quad_perm:[1,0,3,2] row_mask:0xf bank_mask:0xf bound_ctrl:1
	v_lshl_add_u64 v[78:79], v[78:79], 0, s[6:7]
	s_cmpk_gt_i32 s4, 0x7f
	v_add_f32_dpp v124, v124, v124 quad_perm:[2,3,0,1] row_mask:0xf bank_mask:0xf bound_ctrl:1
	s_nop 1
	v_add_f32_dpp v124, v124, v124 row_half_mirror row_mask:0xf bank_mask:0xf bound_ctrl:1
	s_nop 1
	v_add_f32_dpp v124, v124, v124 row_mirror row_mask:0xf bank_mask:0xf bound_ctrl:1
	ds_bpermute_b32 v125, v126, v124
	s_waitcnt lgkmcnt(0)
	v_add_f32_e32 v124, v124, v125
	ds_bpermute_b32 v125, v127, v124
	s_waitcnt lgkmcnt(0)
	v_add_f32_e32 v124, v124, v125
	v_fmamk_f32 v124, v124, 0x3a000000, v194
	v_rsq_f32_e32 v124, v124
	s_nop 0
	v_pk_mul_f32 v[36:37], v[36:37], v[124:125] op_sel_hi:[1,0]
	v_pk_mul_f32 v[38:39], v[38:39], v[124:125] op_sel_hi:[1,0]
	v_pk_mul_f32 v[32:33], v[32:33], v[124:125] op_sel_hi:[1,0]
	v_pk_fma_f32 v[38:39], v[80:81], v[38:39], v[2:3]
	v_pk_fma_f32 v[36:37], v[82:83], v[36:37], v[0:1]
	v_pk_mul_f32 v[34:35], v[34:35], v[124:125] op_sel_hi:[1,0]
	v_pk_fma_f32 v[32:33], v[86:87], v[32:33], v[4:5]
	v_cvt_pk_bf16_f32 v36, v36, v37
	v_cvt_pk_bf16_f32 v37, v38, v39
	v_lshl_add_u64 v[38:39], v[130:131], 0, v[122:123]
	v_pk_fma_f32 v[34:35], v[84:85], v[34:35], v[6:7]
	v_cvt_pk_bf16_f32 v32, v32, v33
	global_store_dwordx2 v[38:39], v[36:37], off
	v_cvt_pk_bf16_f32 v33, v34, v35
	global_store_dwordx2 v[38:39], v[32:33], off offset:512
	v_pk_mul_f32 v[32:33], v[44:45], v[124:125] op_sel_hi:[1,0]
	v_pk_mul_f32 v[34:35], v[46:47], v[124:125] op_sel_hi:[1,0]
	v_pk_fma_f32 v[32:33], v[90:91], v[32:33], v[8:9]
	v_pk_fma_f32 v[34:35], v[88:89], v[34:35], v[10:11]
	v_cvt_pk_bf16_f32 v32, v32, v33
	s_nop 0
	v_cvt_pk_bf16_f32 v33, v34, v35
	global_store_dwordx2 v[38:39], v[32:33], off offset:1024
	v_pk_mul_f32 v[32:33], v[40:41], v[124:125] op_sel_hi:[1,0]
	v_pk_mul_f32 v[34:35], v[42:43], v[124:125] op_sel_hi:[1,0]
	v_pk_fma_f32 v[32:33], v[98:99], v[32:33], v[12:13]
	v_pk_fma_f32 v[34:35], v[96:97], v[34:35], v[14:15]
	v_cvt_pk_bf16_f32 v32, v32, v33
	s_nop 0
	v_cvt_pk_bf16_f32 v33, v34, v35
	global_store_dwordx2 v[38:39], v[32:33], off offset:1536
	v_pk_mul_f32 v[32:33], v[48:49], v[124:125] op_sel_hi:[1,0]
	v_pk_mul_f32 v[34:35], v[50:51], v[124:125] op_sel_hi:[1,0]
	v_pk_fma_f32 v[32:33], v[110:111], v[32:33], v[28:29]
	v_pk_fma_f32 v[34:35], v[108:109], v[34:35], v[30:31]
	v_cvt_pk_bf16_f32 v32, v32, v33
	s_nop 0
	v_cvt_pk_bf16_f32 v33, v34, v35
	global_store_dwordx2 v[38:39], v[32:33], off offset:2048
	v_pk_mul_f32 v[32:33], v[56:57], v[124:125] op_sel_hi:[1,0]
	v_pk_mul_f32 v[34:35], v[58:59], v[124:125] op_sel_hi:[1,0]
	v_pk_fma_f32 v[32:33], v[106:107], v[32:33], v[24:25]
	v_pk_fma_f32 v[34:35], v[104:105], v[34:35], v[26:27]
	v_cvt_pk_bf16_f32 v32, v32, v33
	s_nop 0
	v_cvt_pk_bf16_f32 v33, v34, v35
	global_store_dwordx2 v[38:39], v[32:33], off offset:2560
	v_pk_mul_f32 v[32:33], v[52:53], v[124:125] op_sel_hi:[1,0]
	v_pk_mul_f32 v[34:35], v[54:55], v[124:125] op_sel_hi:[1,0]
	v_pk_fma_f32 v[32:33], v[102:103], v[32:33], v[20:21]
	v_pk_fma_f32 v[34:35], v[100:101], v[34:35], v[22:23]
	v_cvt_pk_bf16_f32 v32, v32, v33
	s_nop 0
	v_cvt_pk_bf16_f32 v33, v34, v35
	global_store_dwordx2 v[38:39], v[32:33], off offset:3072
	v_pk_mul_f32 v[32:33], v[60:61], v[124:125] op_sel_hi:[1,0]
	v_pk_mul_f32 v[34:35], v[62:63], v[124:125] op_sel_hi:[1,0]
	v_pk_fma_f32 v[32:33], v[94:95], v[32:33], v[16:17]
	v_lshl_add_u64 v[60:61], v[112:113], 0, s[8:9]
	v_pk_fma_f32 v[34:35], v[92:93], v[34:35], v[18:19]
	v_cvt_pk_bf16_f32 v32, v32, v33
	v_lshl_add_u64 v[40:41], v[60:61], 0, v[152:153]
	v_cvt_pk_bf16_f32 v33, v34, v35
	global_store_dwordx2 v[38:39], v[32:33], off offset:3584
	global_load_dwordx4 v[36:39], v[40:41], off nt
	s_nop 0
	global_load_dwordx4 v[32:35], v[40:41], off offset:1024 nt
	s_waitcnt vmcnt(1)
; __device__ __forceinline__ unsigned pk2(float lo, float hi) { return pg8::cvt_pk_bf16(lo, hi); }
; __device__ __forceinline__ float rsq_f(float x) { return __builtin_amdgcn_rsqf(x); }
; __device__ __forceinline__ void phase_norm(const float* xp, const float* xs, const float* ng, const float* modl, bf16_t* hb, int gw, int NGW, int lane) {
;     ...
;         for (int k = 0; k < 4; ++k) {
;             f32x4 v[8]; float ss = 0.f;
; #pragma unroll
;             for (int j = 0; j < 8; ++j) { v[j] = ((const f32x4*)(xp + (size_t)(row0 + k) * DM))[lane + 64 * j]; ss += (v[j].x * v[j].x + v[j].y * v[j].y) + (v[j].z * v[j].z + v[j].w * v[j].w); }
;             const float rstd = rsq_f(wave_sum2(ss, lane) * (1.f / DM) + EPS);
; #pragma unroll
;             for (int j = 0; j < 8; ++j) { const int c4 = lane + 64 * j; const f32x4 h = v[j] * rstd * gg[j] + ss0[j]; u32x2 o; o.x = pk2(h.x, h.y); o.y = pk2(h.z, h.w); *(u32x2*)(hb + (size_t)(row0 + k) * DM + c4 * 4) = o; }
;         }
;     }
;     for (int rs = gw; rs < DECB; rs += NGW) {
;         const int row = MP + rs; const float* xr = xs + (size_t)rs * DM;
;         const float* sh = modl + (size_t)(NB + rs) * MODLD; const float* sc = sh + DM;
	v_mov_b32_e32 v44, v37
	s_waitcnt vmcnt(0)
	v_mov_b32_e32 v45, v33
	v_mov_b32_e32 v42, v36
	v_mov_b32_e32 v43, v32
	v_pk_mul_f32 v[44:45], v[44:45], v[44:45]
	v_mov_b32_e32 v46, v39
	v_mov_b32_e32 v47, v35
	v_pk_fma_f32 v[42:43], v[42:43], v[42:43], v[44:45]
	v_mov_b32_e32 v44, v38
	v_mov_b32_e32 v45, v34
	v_pk_mul_f32 v[46:47], v[46:47], v[46:47]
	s_nop 0
	v_pk_fma_f32 v[44:45], v[44:45], v[44:45], v[46:47]
	s_nop 0
	v_pk_add_f32 v[52:53], v[42:43], v[44:45]
	global_load_dwordx4 v[44:47], v[40:41], off offset:2048 nt
	v_pk_add_f32 v[52:53], v[52:53], v[52:53] op_sel:[0,1] op_sel_hi:[1,0]
	s_waitcnt vmcnt(0)
	v_pk_mul_f32 v[42:43], v[46:47], v[46:47]
	v_pk_mul_f32 v[48:49], v[44:45], v[44:45]
	s_nop 0
	v_pk_mov_b32 v[50:51], v[48:49], v[42:43] op_sel:[1,0]
	v_mov_b32_e32 v49, v43
	v_pk_add_f32 v[54:55], v[50:51], v[48:49]
	v_lshl_add_u64 v[48:49], v[60:61], 0, v[120:121]
	global_load_dwordx4 v[40:43], v[40:41], off offset:3072 nt
	v_pk_add_f32 v[54:55], v[54:55], v[54:55] op_sel:[0,1] op_sel_hi:[1,0]
	global_load_dwordx4 v[48:51], v[48:49], off nt
	s_waitcnt vmcnt(0)
	v_mul_f32_e32 v56, v48, v48
	v_mul_f32_e32 v57, v49, v49
	v_mov_b32_e32 v53, v56
	v_mov_b32_e32 v55, v57
	v_pk_add_f32 v[52:53], v[52:53], v[54:55]
	v_mul_f32_e32 v54, v41, v41
	v_mul_f32_e32 v56, v43, v43
	v_mul_f32_e32 v58, v50, v50
	v_mul_f32_e32 v59, v51, v51
	v_pk_fma_f32 v[54:55], v[40:41], v[40:41], v[54:55] op_sel_hi:[1,1,0]
	v_pk_fma_f32 v[56:57], v[42:43], v[42:43], v[56:57] op_sel_hi:[1,1,0]
	v_mov_b32_e32 v55, v58
	v_mov_b32_e32 v57, v59
	v_pk_add_f32 v[54:55], v[54:55], v[56:57]
	s_nop 0
	v_pk_add_f32 v[112:113], v[52:53], v[54:55]
	v_lshl_add_u64 v[52:53], v[60:61], 0, v[116:117]
	global_load_dwordx4 v[56:59], v[52:53], off nt
	v_pk_add_f32 v[112:113], v[112:113], v[112:113] op_sel:[0,1] op_sel_hi:[1,0]
	s_waitcnt vmcnt(0)
	v_pk_mul_f32 v[52:53], v[58:59], v[58:59]
	v_pk_mul_f32 v[54:55], v[56:57], v[56:57]
	s_nop 0
	v_pk_mov_b32 v[62:63], v[54:55], v[52:53] op_sel:[1,0]
	v_mov_b32_e32 v55, v53
	v_lshl_add_u64 v[52:53], v[60:61], 0, v[118:119]
	v_lshl_add_u64 v[60:61], v[60:61], 0, v[114:115]
	v_pk_add_f32 v[116:117], v[62:63], v[54:55]
	global_load_dwordx4 v[52:55], v[52:53], off nt
	s_nop 0
	global_load_dwordx4 v[60:63], v[60:61], off nt
	s_waitcnt vmcnt(0)
	v_mul_f32_e32 v114, v60, v60
	v_mul_f32_e32 v118, v61, v61
	v_mov_b32_e32 v113, v114
	v_pk_add_f32 v[114:115], v[116:117], v[116:117] op_sel:[0,1] op_sel_hi:[1,0]
	v_mul_f32_e32 v116, v55, v55
	v_mov_b32_e32 v115, v118
	v_pk_add_f32 v[112:113], v[112:113], v[114:115]
	v_mul_f32_e32 v114, v53, v53
	v_mul_f32_e32 v119, v62, v62
	v_mul_f32_e32 v120, v63, v63
	v_pk_fma_f32 v[114:115], v[52:53], v[52:53], v[114:115] op_sel_hi:[1,1,0]
	v_pk_fma_f32 v[116:117], v[54:55], v[54:55], v[116:117] op_sel_hi:[1,1,0]
	v_mov_b32_e32 v115, v119
	v_mov_b32_e32 v117, v120
	v_pk_add_f32 v[114:115], v[114:115], v[116:117]
	s_nop 0
	v_pk_add_f32 v[112:113], v[112:113], v[114:115]
	s_nop 0
	v_add_f32_e32 v112, v112, v113
	s_nop 1
	v_add_f32_dpp v112, v112, v112 quad_perm:[1,0,3,2] row_mask:0xf bank_mask:0xf bound_ctrl:1
	s_nop 1
	v_add_f32_dpp v112, v112, v112 quad_perm:[2,3,0,1] row_mask:0xf bank_mask:0xf bound_ctrl:1
	s_nop 1
	v_add_f32_dpp v112, v112, v112 row_half_mirror row_mask:0xf bank_mask:0xf bound_ctrl:1
	s_nop 1
	v_add_f32_dpp v112, v112, v112 row_mirror row_mask:0xf bank_mask:0xf bound_ctrl:1
	ds_bpermute_b32 v113, v126, v112
	s_waitcnt lgkmcnt(0)
	v_add_f32_e32 v112, v112, v113
	ds_bpermute_b32 v113, v127, v112
	s_waitcnt lgkmcnt(0)
	v_add_f32_e32 v112, v112, v113
	v_fmamk_f32 v112, v112, 0x3a000000, v194
	v_rsq_f32_e32 v112, v112
	s_nop 0
	v_pk_mul_f32 v[36:37], v[36:37], v[112:113] op_sel_hi:[1,0]
	v_pk_mul_f32 v[38:39], v[38:39], v[112:113] op_sel_hi:[1,0]
	v_pk_fma_f32 v[0:1], v[82:83], v[36:37], v[0:1]
	v_pk_fma_f32 v[2:3], v[80:81], v[38:39], v[2:3]
	v_cvt_pk_bf16_f32 v0, v0, v1
	s_nop 0
	v_cvt_pk_bf16_f32 v1, v2, v3
	v_lshl_add_u64 v[2:3], v[78:79], 0, v[122:123]
	global_store_dwordx2 v[2:3], v[0:1], off
	v_pk_mul_f32 v[0:1], v[32:33], v[112:113] op_sel_hi:[1,0]
	v_pk_mul_f32 v[32:33], v[34:35], v[112:113] op_sel_hi:[1,0]
	v_pk_fma_f32 v[0:1], v[86:87], v[0:1], v[4:5]
	v_pk_fma_f32 v[6:7], v[84:85], v[32:33], v[6:7]
	v_cvt_pk_bf16_f32 v0, v0, v1
	v_pk_mul_f32 v[4:5], v[46:47], v[112:113] op_sel_hi:[1,0]
	v_cvt_pk_bf16_f32 v1, v6, v7
	global_store_dwordx2 v[2:3], v[0:1], off offset:512
	v_pk_mul_f32 v[0:1], v[44:45], v[112:113] op_sel_hi:[1,0]
	v_pk_fma_f32 v[4:5], v[88:89], v[4:5], v[10:11]
	v_pk_fma_f32 v[0:1], v[90:91], v[0:1], v[8:9]
	s_nop 0
	v_cvt_pk_bf16_f32 v0, v0, v1
	v_cvt_pk_bf16_f32 v1, v4, v5
	global_store_dwordx2 v[2:3], v[0:1], off offset:1024
	v_pk_mul_f32 v[0:1], v[40:41], v[112:113] op_sel_hi:[1,0]
	v_pk_mul_f32 v[4:5], v[42:43], v[112:113] op_sel_hi:[1,0]
	v_pk_fma_f32 v[0:1], v[98:99], v[0:1], v[12:13]
	v_pk_fma_f32 v[4:5], v[96:97], v[4:5], v[14:15]
	v_cvt_pk_bf16_f32 v0, v0, v1
	s_nop 0
	v_cvt_pk_bf16_f32 v1, v4, v5
	global_store_dwordx2 v[2:3], v[0:1], off offset:1536
	v_pk_mul_f32 v[0:1], v[48:49], v[112:113] op_sel_hi:[1,0]
	v_pk_mul_f32 v[4:5], v[50:51], v[112:113] op_sel_hi:[1,0]
	v_pk_fma_f32 v[0:1], v[110:111], v[0:1], v[28:29]
	v_pk_fma_f32 v[4:5], v[108:109], v[4:5], v[30:31]
	v_cvt_pk_bf16_f32 v0, v0, v1
	s_nop 0
	v_cvt_pk_bf16_f32 v1, v4, v5
	global_store_dwordx2 v[2:3], v[0:1], off offset:2048
	v_pk_mul_f32 v[0:1], v[56:57], v[112:113] op_sel_hi:[1,0]
	v_pk_mul_f32 v[4:5], v[58:59], v[112:113] op_sel_hi:[1,0]
	v_pk_fma_f32 v[0:1], v[106:107], v[0:1], v[24:25]
	v_pk_fma_f32 v[4:5], v[104:105], v[4:5], v[26:27]
	v_cvt_pk_bf16_f32 v0, v0, v1
	s_nop 0
	v_cvt_pk_bf16_f32 v1, v4, v5
	global_store_dwordx2 v[2:3], v[0:1], off offset:2560
	v_pk_mul_f32 v[0:1], v[52:53], v[112:113] op_sel_hi:[1,0]
	v_pk_mul_f32 v[4:5], v[54:55], v[112:113] op_sel_hi:[1,0]
	v_pk_fma_f32 v[0:1], v[102:103], v[0:1], v[20:21]
	v_pk_fma_f32 v[4:5], v[100:101], v[4:5], v[22:23]
	v_cvt_pk_bf16_f32 v0, v0, v1
	s_nop 0
	v_cvt_pk_bf16_f32 v1, v4, v5
	global_store_dwordx2 v[2:3], v[0:1], off offset:3072
	v_pk_mul_f32 v[0:1], v[60:61], v[112:113] op_sel_hi:[1,0]
	v_pk_mul_f32 v[4:5], v[62:63], v[112:113] op_sel_hi:[1,0]
	v_pk_fma_f32 v[0:1], v[94:95], v[0:1], v[16:17]
	v_pk_fma_f32 v[4:5], v[92:93], v[4:5], v[18:19]
	v_cvt_pk_bf16_f32 v0, v0, v1
	s_nop 0
	v_cvt_pk_bf16_f32 v1, v4, v5
	global_store_dwordx2 v[2:3], v[0:1], off offset:3584
	s_cbranch_scc1 .LBB0_279
	s_add_i32 s8, s4, 0x2000
	s_ashr_i32 s9, s8, 31
	s_lshl_b64 s[8:9], s[8:9], 12
	s_add_i32 s7, s4, 4
	s_add_i32 s6, s4, 0xfffff800
	v_mov_b32_e32 v33, s9
	s_mul_hi_i32 s9, s7, 0x18000
	s_mul_i32 s7, s7, 0x18000
	v_lshl_or_b32 v32, v128, 3, s8
	s_add_u32 s8, s90, s7
	s_addc_u32 s9, s91, s9
	s_lshl_b64 s[4:5], s[4:5], 13
	v_or_b32_e32 v0, s4, v152
	v_mov_b32_e32 v1, s5
	v_lshl_add_u64 v[0:1], v[76:77], 0, v[0:1]
	s_mov_b64 s[4:5], 0x1000
	v_lshl_add_u64 v[34:35], s[8:9], 0, v[152:153]
	v_lshl_add_u64 v[36:37], v[0:1], 0, s[4:5]
; __device__ __forceinline__ unsigned pk2(float lo, float hi) { return pg8::cvt_pk_bf16(lo, hi); }
; __device__ __forceinline__ float rsq_f(float x) { return __builtin_amdgcn_rsqf(x); }
; __device__ __forceinline__ void phase_norm(const float* xp, const float* xs, const float* ng, const float* modl, bf16_t* hb, int gw, int NGW, int lane) {
;     ...
;     for (int rs = gw; rs < DECB; rs += NGW) {
;         const int row = MP + rs; const float* xr = xs + (size_t)rs * DM;
;         const float* sh = modl + (size_t)(NB + rs) * MODLD; const float* sc = sh + DM;
;         f32x4 v[8]; float ss = 0.f;
; #pragma unroll
;         for (int j = 0; j < 8; ++j) { v[j] = ((const f32x4*)xr)[lane + 64 * j]; ss += (v[j].x * v[j].x + v[j].y * v[j].y) + (v[j].z * v[j].z + v[j].w * v[j].w); }
;         const float rstd = rsq_f(wave_sum2(ss, lane) * (1.f / DM) + EPS);
; #pragma unroll
;         for (int j = 0; j < 8; ++j) { const int c4 = lane + 64 * j; const f32x4 g = ((const f32x4*)ng)[c4], s1 = ((const f32x4*)sc)[c4], s0 = ((const f32x4*)sh)[c4];
;             const f32x4 h = v[j] * rstd * g * (1.f + s1) + s0; u32x2 o; o.x = pk2(h.x, h.y); o.y = pk2(h.z, h.w); *(u32x2*)(hb + (size_t)row * DM + c4 * 4) = o; }
.LBB0_278:
	global_load_dwordx4 v[28:31], v[36:37], off offset:-4096 nt
	global_load_dwordx4 v[0:3], v[36:37], off offset:-3072 nt
	global_load_dwordx4 v[12:15], v[36:37], off offset:-2048 nt
	s_mov_b32 s4, 0x10302000
	s_addk_i32 s6, 0x800
	s_cmpk_lt_i32 s6, 0xf880
	s_waitcnt vmcnt(2)
	v_mov_b32_e32 v6, v29
	s_waitcnt vmcnt(1)
	v_mov_b32_e32 v7, v1
	v_mov_b32_e32 v4, v28
	v_mov_b32_e32 v5, v0
	v_pk_mul_f32 v[6:7], v[6:7], v[6:7]
	v_mov_b32_e32 v8, v31
	v_mov_b32_e32 v9, v3
	v_pk_fma_f32 v[4:5], v[4:5], v[4:5], v[6:7]
	v_mov_b32_e32 v6, v30
	v_mov_b32_e32 v7, v2
	v_pk_mul_f32 v[8:9], v[8:9], v[8:9]
	s_nop 0
	v_pk_fma_f32 v[6:7], v[6:7], v[6:7], v[8:9]
	s_nop 0
	v_pk_add_f32 v[16:17], v[4:5], v[6:7]
	s_waitcnt vmcnt(0)
	v_pk_mul_f32 v[4:5], v[14:15], v[14:15]
	v_pk_mul_f32 v[6:7], v[12:13], v[12:13]
	v_pk_add_f32 v[16:17], v[16:17], v[16:17] op_sel:[0,1] op_sel_hi:[1,0]
	v_pk_mov_b32 v[8:9], v[6:7], v[4:5] op_sel:[1,0]
	v_mov_b32_e32 v7, v5
	v_pk_add_f32 v[18:19], v[8:9], v[6:7]
	global_load_dwordx4 v[8:11], v[36:37], off offset:-1024 nt
	global_load_dwordx4 v[4:7], v[36:37], off nt
	global_load_dwordx4 v[24:27], v[36:37], off offset:1024 nt
	v_pk_add_f32 v[18:19], v[18:19], v[18:19] op_sel:[0,1] op_sel_hi:[1,0]
	s_waitcnt vmcnt(1)
	v_mul_f32_e32 v20, v4, v4
	v_mul_f32_e32 v21, v5, v5
	v_mov_b32_e32 v17, v20
	v_mov_b32_e32 v19, v21
	v_pk_add_f32 v[16:17], v[16:17], v[18:19]
	v_mul_f32_e32 v18, v9, v9
	v_mul_f32_e32 v20, v11, v11
	v_mul_f32_e32 v22, v6, v6
	v_mul_f32_e32 v23, v7, v7
	v_pk_fma_f32 v[18:19], v[8:9], v[8:9], v[18:19] op_sel_hi:[1,1,0]
	v_pk_fma_f32 v[20:21], v[10:11], v[10:11], v[20:21] op_sel_hi:[1,1,0]
	v_mov_b32_e32 v19, v22
	v_mov_b32_e32 v21, v23
	v_pk_add_f32 v[18:19], v[18:19], v[20:21]
	s_nop 0
	v_pk_add_f32 v[38:39], v[16:17], v[18:19]
	s_waitcnt vmcnt(0)
	v_pk_mul_f32 v[16:17], v[26:27], v[26:27]
	v_pk_mul_f32 v[18:19], v[24:25], v[24:25]
	v_pk_add_f32 v[38:39], v[38:39], v[38:39] op_sel:[0,1] op_sel_hi:[1,0]
	v_pk_mov_b32 v[20:21], v[18:19], v[16:17] op_sel:[1,0]
	v_mov_b32_e32 v19, v17
	v_pk_add_f32 v[40:41], v[20:21], v[18:19]
	global_load_dwordx4 v[20:23], v[36:37], off offset:2048 nt
	global_load_dwordx4 v[16:19], v[36:37], off offset:3072 nt
	v_pk_add_f32 v[40:41], v[40:41], v[40:41] op_sel:[0,1] op_sel_hi:[1,0]
	global_load_dwordx4 v[48:51], v[66:67], off nt
	v_lshl_add_u64 v[36:37], v[36:37], 0, s[60:61]
	s_waitcnt vmcnt(1)
	v_mul_f32_e32 v42, v16, v16
	v_mul_f32_e32 v43, v17, v17
	v_mov_b32_e32 v39, v42
	v_mov_b32_e32 v41, v43
	v_pk_add_f32 v[38:39], v[38:39], v[40:41]
	v_mul_f32_e32 v40, v21, v21
	v_mul_f32_e32 v42, v23, v23
	v_mul_f32_e32 v44, v18, v18
	v_mul_f32_e32 v45, v19, v19
	v_pk_fma_f32 v[40:41], v[20:21], v[20:21], v[40:41] op_sel_hi:[1,1,0]
	v_pk_fma_f32 v[42:43], v[22:23], v[22:23], v[42:43] op_sel_hi:[1,1,0]
	v_mov_b32_e32 v41, v44
	v_mov_b32_e32 v43, v45
	v_pk_add_f32 v[40:41], v[40:41], v[42:43]
	v_lshl_add_u64 v[42:43], v[64:65], 0, v[34:35]
	v_add_co_u32_e32 v44, vcc, s4, v42
	s_mov_b32 s4, 0x10303000
	s_nop 0
	v_addc_co_u32_e32 v45, vcc, 0, v43, vcc
	v_pk_add_f32 v[38:39], v[38:39], v[40:41]
	v_add_co_u32_e32 v40, vcc, s4, v42
	s_mov_b32 s4, 0x10300000
	s_nop 0
	v_addc_co_u32_e32 v41, vcc, 0, v43, vcc
	v_add_co_u32_e32 v46, vcc, s4, v42
	s_mov_b32 s4, 0x10301000
	s_nop 0
	v_addc_co_u32_e32 v47, vcc, 0, v43, vcc
	v_add_co_u32_e32 v42, vcc, s4, v42
	global_load_dwordx4 v[52:55], v[40:41], off offset:-4096 nt
	s_nop 0
	v_addc_co_u32_e32 v43, vcc, 0, v43, vcc
	global_load_dwordx4 v[56:59], v[42:43], off offset:-4096 nt
	v_add_f32_e32 v38, v38, v39
	s_mov_b32 s4, 0x11b00000
	s_nop 0
	v_add_f32_dpp v38, v38, v38 quad_perm:[1,0,3,2] row_mask:0xf bank_mask:0xf bound_ctrl:1
	s_nop 1
	v_add_f32_dpp v38, v38, v38 quad_perm:[2,3,0,1] row_mask:0xf bank_mask:0xf bound_ctrl:1
	s_nop 1
	v_add_f32_dpp v38, v38, v38 row_half_mirror row_mask:0xf bank_mask:0xf bound_ctrl:1
	s_nop 1
	v_add_f32_dpp v38, v38, v38 row_mirror row_mask:0xf bank_mask:0xf bound_ctrl:1
	ds_bpermute_b32 v39, v126, v38
	s_waitcnt lgkmcnt(0)
	v_add_f32_e32 v38, v38, v39
	ds_bpermute_b32 v39, v127, v38
	s_waitcnt lgkmcnt(0)
	v_add_f32_e32 v38, v38, v39
	v_fmamk_f32 v38, v38, 0x3a000000, v194
	v_rsq_f32_e32 v38, v38
	s_nop 0
	v_pk_mul_f32 v[30:31], v[30:31], v[38:39] op_sel_hi:[1,0]
	v_pk_mul_f32 v[28:29], v[28:29], v[38:39] op_sel_hi:[1,0]
	s_waitcnt vmcnt(2)
	v_pk_mul_f32 v[30:31], v[50:51], v[30:31]
	v_pk_mul_f32 v[28:29], v[48:49], v[28:29]
	v_pk_mul_f32 v[0:1], v[0:1], v[38:39] op_sel_hi:[1,0]
	v_pk_mul_f32 v[2:3], v[2:3], v[38:39] op_sel_hi:[1,0]
	v_pk_mul_f32 v[14:15], v[14:15], v[38:39] op_sel_hi:[1,0]
	v_pk_mul_f32 v[12:13], v[12:13], v[38:39] op_sel_hi:[1,0]
	v_pk_mul_f32 v[10:11], v[10:11], v[38:39] op_sel_hi:[1,0]
	v_pk_mul_f32 v[8:9], v[8:9], v[38:39] op_sel_hi:[1,0]
	v_pk_mul_f32 v[6:7], v[6:7], v[38:39] op_sel_hi:[1,0]
	v_pk_mul_f32 v[4:5], v[4:5], v[38:39] op_sel_hi:[1,0]
	s_waitcnt vmcnt(1)
	v_pk_add_f32 v[50:51], v[52:53], 1.0 op_sel_hi:[1,0]
	v_pk_add_f32 v[48:49], v[54:55], 1.0 op_sel_hi:[1,0]
	s_waitcnt vmcnt(0)
; __device__ __forceinline__ unsigned pk2(float lo, float hi) { return pg8::cvt_pk_bf16(lo, hi); }
; __device__ __forceinline__ float rsq_f(float x) { return __builtin_amdgcn_rsqf(x); }
; __device__ __forceinline__ void phase_norm(const float* xp, const float* xs, const float* ng, const float* modl, bf16_t* hb, int gw, int NGW, int lane) {
;     ...
;     for (int rs = gw; rs < DECB; rs += NGW) {
;         const int row = MP + rs; const float* xr = xs + (size_t)rs * DM;
;         const float* sh = modl + (size_t)(NB + rs) * MODLD; const float* sc = sh + DM;
;         f32x4 v[8]; float ss = 0.f;
; #pragma unroll
;         for (int j = 0; j < 8; ++j) { v[j] = ((const f32x4*)xr)[lane + 64 * j]; ss += (v[j].x * v[j].x + v[j].y * v[j].y) + (v[j].z * v[j].z + v[j].w * v[j].w); }
;         const float rstd = rsq_f(wave_sum2(ss, lane) * (1.f / DM) + EPS);
; #pragma unroll
;         for (int j = 0; j < 8; ++j) { const int c4 = lane + 64 * j; const f32x4 g = ((const f32x4*)ng)[c4], s1 = ((const f32x4*)sc)[c4], s0 = ((const f32x4*)sh)[c4];
;             const f32x4 h = v[j] * rstd * g * (1.f + s1) + s0; u32x2 o; o.x = pk2(h.x, h.y); o.y = pk2(h.z, h.w); *(u32x2*)(hb + (size_t)row * DM + c4 * 4) = o; }
	v_pk_fma_f32 v[28:29], v[50:51], v[28:29], v[56:57]
	v_pk_fma_f32 v[48:49], v[48:49], v[30:31], v[58:59]
	v_cvt_pk_bf16_f32 v30, v28, v29
	v_lshl_add_u64 v[28:29], v[64:65], 0, v[32:33]
	v_add_co_u32_e32 v28, vcc, s4, v28
	v_cvt_pk_bf16_f32 v31, v48, v49
	s_mov_b64 s[4:5], 0x800000
	s_nop 0
	v_addc_co_u32_e32 v29, vcc, 0, v29, vcc
	global_store_dwordx2 v[28:29], v[30:31], off
	global_load_dwordx4 v[48:51], v[66:67], off offset:1024 nt
	global_load_dwordx4 v[52:55], v[44:45], off offset:1024 nt
	global_load_dwordx4 v[56:59], v[46:47], off offset:1024 nt
	v_lshl_add_u64 v[32:33], v[32:33], 0, s[4:5]
	s_mov_b64 s[4:5], 0xc000000
	v_lshl_add_u64 v[34:35], v[34:35], 0, s[4:5]
	s_waitcnt vmcnt(2)
	v_pk_mul_f32 v[0:1], v[48:49], v[0:1]
	s_waitcnt vmcnt(1)
	v_pk_add_f32 v[48:49], v[52:53], 1.0 op_sel_hi:[1,0]
	v_pk_mul_f32 v[2:3], v[50:51], v[2:3]
	v_pk_add_f32 v[30:31], v[54:55], 1.0 op_sel_hi:[1,0]
	s_waitcnt vmcnt(0)
	v_pk_fma_f32 v[0:1], v[48:49], v[0:1], v[56:57]
	v_pk_fma_f32 v[2:3], v[30:31], v[2:3], v[58:59]
	v_cvt_pk_bf16_f32 v0, v0, v1
	s_nop 0
	v_cvt_pk_bf16_f32 v1, v2, v3
	global_store_dwordx2 v[28:29], v[0:1], off offset:512
	global_load_dwordx4 v[0:3], v[66:67], off offset:2048 nt
	s_nop 0
	global_load_dwordx4 v[48:51], v[44:45], off offset:2048 nt
	global_load_dwordx4 v[52:55], v[46:47], off offset:2048 nt
	s_waitcnt vmcnt(2)
	v_pk_mul_f32 v[0:1], v[12:13], v[0:1]
	v_pk_mul_f32 v[2:3], v[14:15], v[2:3]
	s_waitcnt vmcnt(1)
	v_pk_add_f32 v[14:15], v[48:49], 1.0 op_sel_hi:[1,0]
	v_pk_add_f32 v[12:13], v[50:51], 1.0 op_sel_hi:[1,0]
	s_waitcnt vmcnt(0)
	v_pk_fma_f32 v[0:1], v[0:1], v[14:15], v[52:53]
	v_pk_fma_f32 v[2:3], v[2:3], v[12:13], v[54:55]
	v_cvt_pk_bf16_f32 v0, v0, v1
	s_nop 0
	v_cvt_pk_bf16_f32 v1, v2, v3
	global_store_dwordx2 v[28:29], v[0:1], off offset:1024
	global_load_dwordx4 v[0:3], v[66:67], off offset:3072 nt
	s_nop 0
	global_load_dwordx4 v[12:15], v[44:45], off offset:3072 nt
	s_nop 0
	global_load_dwordx4 v[44:47], v[46:47], off offset:3072 nt
	s_waitcnt vmcnt(2)
	v_pk_mul_f32 v[0:1], v[8:9], v[0:1]
	v_pk_mul_f32 v[2:3], v[10:11], v[2:3]
	s_waitcnt vmcnt(1)
	v_pk_add_f32 v[10:11], v[12:13], 1.0 op_sel_hi:[1,0]
	v_pk_add_f32 v[8:9], v[14:15], 1.0 op_sel_hi:[1,0]
	s_waitcnt vmcnt(0)
	v_pk_fma_f32 v[0:1], v[0:1], v[10:11], v[44:45]
	v_pk_fma_f32 v[2:3], v[2:3], v[8:9], v[46:47]
	v_cvt_pk_bf16_f32 v0, v0, v1
	s_nop 0
	v_cvt_pk_bf16_f32 v1, v2, v3
	global_store_dwordx2 v[28:29], v[0:1], off offset:1536
	global_load_dwordx4 v[0:3], v[68:69], off nt
	s_nop 0
	global_load_dwordx4 v[8:11], v[40:41], off nt
	global_load_dwordx4 v[12:15], v[42:43], off nt
	s_waitcnt vmcnt(2)
	v_pk_mul_f32 v[0:1], v[4:5], v[0:1]
	v_pk_mul_f32 v[2:3], v[6:7], v[2:3]
	s_waitcnt vmcnt(1)
	v_pk_add_f32 v[6:7], v[8:9], 1.0 op_sel_hi:[1,0]
	v_pk_add_f32 v[4:5], v[10:11], 1.0 op_sel_hi:[1,0]
	s_waitcnt vmcnt(0)
	v_pk_fma_f32 v[0:1], v[0:1], v[6:7], v[12:13]
	v_pk_fma_f32 v[2:3], v[2:3], v[4:5], v[14:15]
	v_cvt_pk_bf16_f32 v0, v0, v1
	v_pk_mul_f32 v[14:15], v[24:25], v[38:39] op_sel_hi:[1,0]
	v_cvt_pk_bf16_f32 v1, v2, v3
	global_store_dwordx2 v[28:29], v[0:1], off offset:2048
	global_load_dwordx4 v[0:3], v[70:71], off nt
	s_nop 0
	global_load_dwordx4 v[4:7], v[40:41], off offset:1024 nt
	global_load_dwordx4 v[8:11], v[42:43], off offset:1024 nt
	v_pk_mul_f32 v[12:13], v[26:27], v[38:39] op_sel_hi:[1,0]
	s_waitcnt vmcnt(2)
	v_pk_mul_f32 v[0:1], v[14:15], v[0:1]
	s_waitcnt vmcnt(1)
	v_pk_add_f32 v[4:5], v[4:5], 1.0 op_sel_hi:[1,0]
	v_pk_mul_f32 v[2:3], v[12:13], v[2:3]
	v_pk_add_f32 v[6:7], v[6:7], 1.0 op_sel_hi:[1,0]
	s_waitcnt vmcnt(0)
	v_pk_fma_f32 v[0:1], v[0:1], v[4:5], v[8:9]
	v_pk_fma_f32 v[2:3], v[2:3], v[6:7], v[10:11]
	v_cvt_pk_bf16_f32 v0, v0, v1
	v_pk_mul_f32 v[14:15], v[20:21], v[38:39] op_sel_hi:[1,0]
	v_cvt_pk_bf16_f32 v1, v2, v3
	global_store_dwordx2 v[28:29], v[0:1], off offset:2560
	global_load_dwordx4 v[0:3], v[72:73], off nt
	s_nop 0
	global_load_dwordx4 v[4:7], v[40:41], off offset:2048 nt
	global_load_dwordx4 v[8:11], v[42:43], off offset:2048 nt
	v_pk_mul_f32 v[12:13], v[22:23], v[38:39] op_sel_hi:[1,0]
	s_waitcnt vmcnt(2)
	v_pk_mul_f32 v[0:1], v[14:15], v[0:1]
	s_waitcnt vmcnt(1)
	v_pk_add_f32 v[4:5], v[4:5], 1.0 op_sel_hi:[1,0]
	v_pk_mul_f32 v[2:3], v[12:13], v[2:3]
	v_pk_add_f32 v[6:7], v[6:7], 1.0 op_sel_hi:[1,0]
	s_waitcnt vmcnt(0)
	v_pk_fma_f32 v[0:1], v[0:1], v[4:5], v[8:9]
	v_pk_fma_f32 v[2:3], v[2:3], v[6:7], v[10:11]
	v_cvt_pk_bf16_f32 v0, v0, v1
	v_pk_mul_f32 v[14:15], v[16:17], v[38:39] op_sel_hi:[1,0]
	v_cvt_pk_bf16_f32 v1, v2, v3
	global_store_dwordx2 v[28:29], v[0:1], off offset:3072
	global_load_dwordx4 v[0:3], v[74:75], off nt
	s_nop 0
	global_load_dwordx4 v[4:7], v[40:41], off offset:3072 nt
	global_load_dwordx4 v[8:11], v[42:43], off offset:3072 nt
	v_pk_mul_f32 v[12:13], v[18:19], v[38:39] op_sel_hi:[1,0]
	s_waitcnt vmcnt(2)
	v_pk_mul_f32 v[0:1], v[14:15], v[0:1]
	s_waitcnt vmcnt(1)
	v_pk_add_f32 v[4:5], v[4:5], 1.0 op_sel_hi:[1,0]
	v_pk_mul_f32 v[2:3], v[12:13], v[2:3]
	v_pk_add_f32 v[6:7], v[6:7], 1.0 op_sel_hi:[1,0]
	s_waitcnt vmcnt(0)
	v_pk_fma_f32 v[0:1], v[0:1], v[4:5], v[8:9]
	v_pk_fma_f32 v[2:3], v[2:3], v[6:7], v[10:11]
	v_cvt_pk_bf16_f32 v0, v0, v1
	s_nop 0
	v_cvt_pk_bf16_f32 v1, v2, v3
	global_store_dwordx2 v[28:29], v[0:1], off offset:3584
	s_cbranch_scc1 .LBB0_278

; __device__ __forceinline__ float rsq_f(float x) { return __builtin_amdgcn_rsqf(x); }
; __device__ __forceinline__ void final_row(const f32x4 (&v)[8], const f32x4 (&g)[8], float* orow, int lane) {
;     float ss = 0.f;
; #pragma unroll
;     for (int j = 0; j < 8; ++j) ss += (v[j].x * v[j].x + v[j].y * v[j].y) + (v[j].z * v[j].z + v[j].w * v[j].w);
;     const float rstd = rsq_f(wave_sum(ss) * (1.f / DM) + EPS);
; __device__ __forceinline__ void phase_final(const float* x, const float* g, float* out, int gw, int NGW, int lane) {
;     f32x4 gg[8];
; #pragma unroll
;     for (int j = 0; j < 8; ++j) gg[j] = ((const f32x4*)g)[lane + 64 * j];
;     const int row0 = gw * 4;
;     f32x4 v[8], w[8];
; #pragma unroll
;     for (int j = 0; j < 8; ++j) v[j] = ((const f32x4*)(x + (size_t)row0 * DM))[lane + 64 * j];
; #pragma unroll
;     for (int k = 0; k < 4; ++k) {
;         if (k < 3) {
; #pragma unroll
;             for (int j = 0; j < 8; ++j) w[j] = ((const f32x4*)(x + (size_t)(row0 + k + 1) * DM))[lane + 64 * j];
.LBB0_703:
	s_mov_b32 s4, -1
	v_mov_b32_e32 v99, 0
	s_waitcnt vmcnt(0)
	v_mbcnt_lo_u32_b32 v0, s4, 0
	v_mbcnt_hi_u32_b32 v0, s4, v0
	v_or_b32_e32 v2, s3, v0
	s_mov_b64 s[4:5], 0x1c200000
	v_mov_b64_e32 v[0:1], s[0:1]
	flat_load_dwordx2 v[100:101], v[0:1] offset:152
	flat_load_dwordx4 v[30:33], v[0:1] offset:136
	v_readfirstlane_b32 s0, v2
	s_lshl_b32 s1, s2, 3
	s_ashr_i32 s0, s0, 6
	s_add_i32 s0, s0, s1
	s_lshl_b32 s2, s0, 2
	s_ashr_i32 s3, s2, 31
	v_and_b32_e32 v0, 63, v2
	s_lshl_b64 s[6:7], s[2:3], 13
	v_lshlrev_b32_e32 v98, 4, v0
	v_mov_b32_e32 v107, v99
	v_or_b32_e32 v106, 0x1400, v98
	v_mov_b32_e32 v105, v99
	v_or_b32_e32 v104, 0x1800, v98
	v_mov_b32_e32 v109, v99
	v_or_b32_e32 v108, 0x1000, v98
	v_mov_b32_e32 v111, v99
	v_or_b32_e32 v110, 0x1c00, v98
	v_xor_b32_e32 v4, 2, v192
	v_xor_b32_e32 v5, 4, v192
	v_xor_b32_e32 v6, 8, v192
	v_xor_b32_e32 v7, 16, v192
	v_mov_b32_e32 v114, 0x358637bd
	s_movk_i32 s8, 0x1000
	s_waitcnt vmcnt(0) lgkmcnt(0)
	v_lshl_add_u64 v[112:113], v[100:101], 0, s[4:5]
	v_lshl_add_u64 v[0:1], v[112:113], 0, s[6:7]
	v_lshl_add_u64 v[2:3], v[0:1], 0, v[98:99]
	global_load_dwordx4 v[42:45], v[2:3], off nt
	global_load_dwordx4 v[38:41], v[2:3], off offset:1024 nt
	global_load_dwordx4 v[46:49], v[2:3], off offset:2048 nt
	global_load_dwordx4 v[50:53], v[2:3], off offset:3072 nt
	v_lshl_add_u64 v[2:3], v[0:1], 0, v[106:107]
	global_load_dwordx4 v[54:57], v[2:3], off nt
	v_lshl_add_u64 v[2:3], v[0:1], 0, v[104:105]
	global_load_dwordx4 v[58:61], v[2:3], off nt
	v_lshl_add_u64 v[2:3], v[0:1], 0, v[108:109]
	global_load_dwordx4 v[62:65], v[2:3], off nt
	v_lshl_add_u64 v[0:1], v[0:1], 0, v[110:111]
	global_load_dwordx4 v[34:37], v[0:1], off nt
	v_and_b32_e32 v2, 64, v192
	v_xor_b32_e32 v3, 1, v192
	v_add_u32_e32 v1, 64, v2
	v_cmp_lt_i32_e32 vcc, v3, v1
	s_or_b32 s4, s2, 1
	s_ashr_i32 s5, s4, 31
	v_cndmask_b32_e32 v2, v192, v3, vcc
	v_cmp_lt_i32_e32 vcc, v4, v1
	v_xor_b32_e32 v0, 32, v192
	s_lshl_b64 s[4:5], s[4:5], 13
	v_cndmask_b32_e32 v3, v192, v4, vcc
	v_cmp_lt_i32_e32 vcc, v5, v1
	v_lshl_add_u64 v[90:91], v[112:113], 0, s[4:5]
	v_lshl_add_u64 v[70:71], v[30:31], 0, v[98:99]
	v_cndmask_b32_e32 v4, v192, v5, vcc
	v_cmp_lt_i32_e32 vcc, v6, v1
	v_lshl_add_u64 v[72:73], v[30:31], 0, v[108:109]
	v_lshl_add_u64 v[78:79], v[30:31], 0, v[106:107]
	v_cndmask_b32_e32 v5, v192, v6, vcc
	v_cmp_lt_i32_e32 vcc, v7, v1
	v_lshl_add_u64 v[80:81], v[30:31], 0, v[104:105]
	v_lshl_add_u64 v[84:85], v[90:91], 0, v[98:99]
	v_cndmask_b32_e32 v6, v192, v7, vcc
	v_cmp_lt_i32_e32 vcc, v0, v1
	v_lshlrev_b32_e32 v115, 2, v2
	v_lshlrev_b32_e32 v116, 2, v3
	v_cndmask_b32_e32 v0, v192, v0, vcc
	v_lshlrev_b32_e32 v117, 2, v4
	v_lshlrev_b32_e32 v118, 2, v5
	v_lshlrev_b32_e32 v119, 2, v6
	v_lshlrev_b32_e32 v120, 2, v0
	v_lshl_add_u64 v[82:83], v[30:31], 0, v[110:111]
	global_load_dwordx4 v[66:69], v[84:85], off offset:1024 nt
	global_load_dwordx4 v[74:77], v[84:85], off nt
	global_load_dwordx4 v[0:3], v[70:71], off nt
	global_load_dwordx4 v[4:7], v[70:71], off offset:1024 nt
	global_load_dwordx4 v[8:11], v[70:71], off offset:2048 nt
	global_load_dwordx4 v[12:15], v[70:71], off offset:3072 nt
	global_load_dwordx4 v[16:19], v[72:73], off nt
	global_load_dwordx4 v[20:23], v[78:79], off nt
	global_load_dwordx4 v[24:27], v[80:81], off nt
	global_load_dwordx4 v[28:31], v[82:83], off nt
	s_nop 0
	global_load_dwordx4 v[70:73], v[84:85], off offset:3072 nt
	global_load_dwordx4 v[78:81], v[84:85], off offset:2048 nt
	v_lshl_add_u64 v[82:83], v[90:91], 0, v[106:107]
	v_lshl_add_u64 v[92:93], v[90:91], 0, v[110:111]
	v_lshl_add_u64 v[102:103], v[32:33], 0, v[98:99]
	v_lshl_add_u64 v[122:123], v[102:103], 0, s[6:7]
	s_or_b32 s6, s2, 2
	s_ashr_i32 s7, s6, 31
	s_lshl_b64 s[6:7], s[6:7], 13
	s_or_b32 s2, s2, 3
	s_ashr_i32 s3, s2, 31
	s_lshl_b64 s[2:3], s[2:3], 13
	s_cmpk_gt_i32 s0, 0x7f
	s_waitcnt vmcnt(19)
	v_mov_b32_e32 v86, v43
	s_waitcnt vmcnt(18)
	v_mov_b32_e32 v87, v39
	v_mov_b32_e32 v94, v45
	v_mov_b32_e32 v95, v41
	v_mov_b32_e32 v84, v42
	v_mov_b32_e32 v85, v38
	v_mov_b32_e32 v88, v44
	v_mov_b32_e32 v89, v40
	s_waitcnt vmcnt(17)
	v_pk_mul_f32 v[96:97], v[48:49], v[48:49]
	v_pk_mul_f32 v[124:125], v[46:47], v[46:47]
	v_pk_mul_f32 v[86:87], v[86:87], v[86:87]
	v_pk_mul_f32 v[94:95], v[94:95], v[94:95]
	v_pk_mov_b32 v[138:139], v[124:125], v[96:97] op_sel:[1,0]
	v_mov_b32_e32 v125, v97
	v_pk_fma_f32 v[84:85], v[84:85], v[84:85], v[86:87]
	v_pk_fma_f32 v[86:87], v[88:89], v[88:89], v[94:95]
	s_waitcnt vmcnt(16)
	v_mul_f32_e32 v126, v50, v50
	v_mul_f32_e32 v128, v52, v52
	v_pk_add_f32 v[88:89], v[138:139], v[124:125]
	v_pk_add_f32 v[84:85], v[84:85], v[86:87]
	v_pk_fma_f32 v[96:97], v[50:51], v[50:51], v[126:127] op_sel_hi:[1,1,0]
	v_pk_fma_f32 v[126:127], v[52:53], v[52:53], v[128:129] op_sel_hi:[1,1,0]
	v_pk_add_f32 v[86:87], v[88:89], v[88:89] op_sel_hi:[0,1]
	v_pk_add_f32 v[84:85], v[84:85], v[84:85] op_sel_hi:[0,1]
	s_waitcnt vmcnt(15)
	v_pk_mul_f32 v[130:131], v[56:57], v[56:57]
	v_pk_mul_f32 v[132:133], v[54:55], v[54:55]
	s_waitcnt vmcnt(13)
	v_mul_f32_e32 v96, v62, v62
	v_mul_f32_e32 v126, v63, v63
	v_mul_f32_e32 v86, v64, v64
	v_mul_f32_e32 v84, v65, v65
	v_pk_mov_b32 v[128:129], v[132:133], v[130:131] op_sel:[1,0]
	v_mov_b32_e32 v133, v131
	v_pk_add_f32 v[88:89], v[96:97], v[126:127]
	v_pk_add_f32 v[84:85], v[86:87], v[84:85]
	v_mul_f32_e32 v134, v58, v58
	v_mul_f32_e32 v136, v60, v60
	v_pk_add_f32 v[94:95], v[128:129], v[132:133]
	v_pk_add_f32 v[84:85], v[88:89], v[84:85]
	v_pk_fma_f32 v[130:131], v[58:59], v[58:59], v[134:135] op_sel_hi:[1,1,0]
	v_pk_fma_f32 v[134:135], v[60:61], v[60:61], v[136:137] op_sel_hi:[1,1,0]
	v_pk_add_f32 v[94:95], v[94:95], v[94:95] op_sel_hi:[0,1]
	v_pk_add_f32 v[84:85], v[84:85], v[84:85] op_sel_hi:[0,1]
	s_waitcnt vmcnt(12)
; __device__ __forceinline__ float rsq_f(float x) { return __builtin_amdgcn_rsqf(x); }
; __device__ __forceinline__ void final_row(const f32x4 (&v)[8], const f32x4 (&g)[8], float* orow, int lane) {
;     float ss = 0.f;
; #pragma unroll
;     for (int j = 0; j < 8; ++j) ss += (v[j].x * v[j].x + v[j].y * v[j].y) + (v[j].z * v[j].z + v[j].w * v[j].w);
;     const float rstd = rsq_f(wave_sum(ss) * (1.f / DM) + EPS);
; #pragma unroll
;     for (int j = 0; j < 8; ++j) ((f32x4*)orow)[lane + 64 * j] = v[j] * rstd * g[j];
; __device__ __forceinline__ void phase_final(const float* x, const float* g, float* out, int gw, int NGW, int lane) {
;     ...
;     for (int j = 0; j < 8; ++j) v[j] = ((const f32x4*)(x + (size_t)row0 * DM))[lane + 64 * j];
; #pragma unroll
;     for (int k = 0; k < 4; ++k) {
;         if (k < 3) {
; #pragma unroll
;             for (int j = 0; j < 8; ++j) w[j] = ((const f32x4*)(x + (size_t)(row0 + k + 1) * DM))[lane + 64 * j];
;         }
;         final_row(v, gg, out + (size_t)(row0 + k) * DM, lane);
; #pragma unroll
;         for (int j = 0; j < 8; ++j) v[j] = w[j];
	v_mul_f32_e32 v130, v34, v34
	v_mul_f32_e32 v134, v35, v35
	v_mul_f32_e32 v94, v36, v36
	v_mul_f32_e32 v84, v37, v37
	v_pk_add_f32 v[96:97], v[130:131], v[134:135]
	v_pk_add_f32 v[84:85], v[94:95], v[84:85]
	v_lshl_add_u64 v[86:87], v[90:91], 0, v[108:109]
	v_pk_add_f32 v[84:85], v[96:97], v[84:85]
	v_lshl_add_u64 v[94:95], v[90:91], 0, v[104:105]
	v_add_f32_e32 v96, v84, v85
	ds_bpermute_b32 v97, v115, v96
	global_load_dwordx4 v[82:85], v[82:83], off nt
	s_nop 0
	global_load_dwordx4 v[86:89], v[86:87], off nt
	s_waitcnt vmcnt(13)
	v_mov_b32_e32 v128, v67
	s_waitcnt vmcnt(12)
	v_mov_b32_e32 v129, v75
	v_mov_b32_e32 v132, v69
	s_waitcnt lgkmcnt(0)
	v_add_f32_e32 v121, v96, v97
	global_load_dwordx4 v[90:93], v[92:93], off nt
	s_nop 0
	global_load_dwordx4 v[94:97], v[94:95], off nt
	ds_bpermute_b32 v126, v116, v121
	v_mov_b32_e32 v133, v77
	v_mov_b32_e32 v127, v74
	v_mov_b32_e32 v131, v76
	v_pk_mul_f32 v[128:129], v[128:129], v[128:129]
	s_waitcnt lgkmcnt(0)
	v_add_f32_e32 v121, v121, v126
	ds_bpermute_b32 v130, v117, v121
	v_mov_b32_e32 v126, v66
	v_pk_mul_f32 v[132:133], v[132:133], v[132:133]
	v_pk_fma_f32 v[126:127], v[126:127], v[126:127], v[128:129]
	s_waitcnt vmcnt(4)
	v_pk_mul_f32 v[136:137], v[78:79], v[78:79]
	s_waitcnt lgkmcnt(0)
	v_add_f32_e32 v121, v121, v130
	ds_bpermute_b32 v134, v118, v121
	v_mov_b32_e32 v130, v68
	v_pk_fma_f32 v[128:129], v[130:131], v[130:131], v[132:133]
	v_add_co_u32_e32 v124, vcc, s8, v122
	s_waitcnt lgkmcnt(0)
	v_add_f32_e32 v121, v121, v134
	ds_bpermute_b32 v138, v119, v121
	v_pk_mul_f32 v[134:135], v[80:81], v[80:81]
	v_pk_add_f32 v[126:127], v[126:127], v[128:129]
	v_addc_co_u32_e32 v125, vcc, 0, v123, vcc
	s_waitcnt lgkmcnt(0)
	v_add_f32_e32 v121, v121, v138
	ds_bpermute_b32 v140, v120, v121
	v_pk_mov_b32 v[138:139], v[136:137], v[134:135] op_sel:[1,0]
	v_mov_b32_e32 v137, v135
	v_pk_add_f32 v[132:133], v[138:139], v[136:137]
	v_pk_add_f32 v[126:127], v[126:127], v[126:127] op_sel_hi:[0,1]
	s_waitcnt lgkmcnt(0)
	v_add_f32_e32 v121, v121, v140
	v_fmamk_f32 v121, v121, 0x3a000000, v114
	v_rsq_f32_e32 v130, v121
	s_waitcnt vmcnt(2)
	v_mul_f32_e32 v126, v89, v89
	v_pk_mul_f32 v[42:43], v[42:43], v[130:131] op_sel_hi:[1,0]
	v_pk_mul_f32 v[44:45], v[44:45], v[130:131] op_sel_hi:[1,0]
	v_pk_mul_f32 v[128:129], v[38:39], v[130:131] op_sel_hi:[1,0]
	v_pk_mul_f32 v[134:135], v[40:41], v[130:131] op_sel_hi:[1,0]
	v_pk_mul_f32 v[46:47], v[46:47], v[130:131] op_sel_hi:[1,0]
	v_pk_mul_f32 v[48:49], v[48:49], v[130:131] op_sel_hi:[1,0]
	v_pk_mul_f32 v[50:51], v[50:51], v[130:131] op_sel_hi:[1,0]
	v_pk_mul_f32 v[52:53], v[52:53], v[130:131] op_sel_hi:[1,0]
	v_pk_mul_f32 v[62:63], v[62:63], v[130:131] op_sel_hi:[1,0]
	v_pk_mul_f32 v[64:65], v[64:65], v[130:131] op_sel_hi:[1,0]
	v_pk_mul_f32 v[136:137], v[54:55], v[130:131] op_sel_hi:[1,0]
	v_pk_mul_f32 v[138:139], v[56:57], v[130:131] op_sel_hi:[1,0]
	v_pk_mul_f32 v[140:141], v[58:59], v[130:131] op_sel_hi:[1,0]
	v_pk_mul_f32 v[142:143], v[60:61], v[130:131] op_sel_hi:[1,0]
	v_pk_mul_f32 v[40:41], v[2:3], v[44:45]
	v_pk_mul_f32 v[38:39], v[0:1], v[42:43]
	v_pk_mul_f32 v[44:45], v[6:7], v[134:135]
	v_pk_mul_f32 v[42:43], v[4:5], v[128:129]
	v_pk_mul_f32 v[48:49], v[10:11], v[48:49]
	v_pk_mul_f32 v[46:47], v[8:9], v[46:47]
	v_pk_mul_f32 v[52:53], v[14:15], v[52:53]
	v_pk_mul_f32 v[50:51], v[12:13], v[50:51]
	v_pk_mul_f32 v[56:57], v[18:19], v[64:65]
	v_pk_mul_f32 v[54:55], v[16:17], v[62:63]
	v_pk_mul_f32 v[60:61], v[22:23], v[138:139]
	v_pk_mul_f32 v[58:59], v[20:21], v[136:137]
	v_pk_mul_f32 v[64:65], v[26:27], v[142:143]
	v_pk_mul_f32 v[62:63], v[24:25], v[140:141]
	global_store_dwordx4 v[122:123], v[38:41], off nt
	global_store_dwordx4 v[122:123], v[42:45], off offset:1024 nt
	global_store_dwordx4 v[122:123], v[46:49], off offset:2048 nt
	global_store_dwordx4 v[122:123], v[50:53], off offset:3072 nt
	global_store_dwordx4 v[124:125], v[54:57], off nt
	global_store_dwordx4 v[124:125], v[58:61], off offset:1024 nt
	global_store_dwordx4 v[124:125], v[62:65], off offset:2048 nt
	v_pk_add_f32 v[38:39], v[132:133], v[132:133] op_sel_hi:[0,1]
	v_mul_f32_e32 v38, v70, v70
	v_pk_fma_f32 v[40:41], v[70:71], v[70:71], v[38:39] op_sel_hi:[1,1,0]
	v_mul_f32_e32 v38, v72, v72
	v_pk_fma_f32 v[42:43], v[72:73], v[72:73], v[38:39] op_sel_hi:[1,1,0]
	v_mul_f32_e32 v40, v86, v86
	v_mul_f32_e32 v42, v87, v87
	v_mul_f32_e32 v38, v88, v88
	v_pk_add_f32 v[40:41], v[40:41], v[42:43]
	v_pk_add_f32 v[38:39], v[38:39], v[126:127]
	v_pk_mul_f32 v[42:43], v[82:83], v[82:83]
	v_pk_add_f32 v[38:39], v[40:41], v[38:39]
	v_pk_mul_f32 v[40:41], v[84:85], v[84:85]
	v_pk_add_f32 v[38:39], v[38:39], v[38:39] op_sel_hi:[0,1]
	v_pk_mov_b32 v[44:45], v[42:43], v[40:41] op_sel:[1,0]
	v_mov_b32_e32 v43, v41
	s_waitcnt vmcnt(7)
	v_mul_f32_e32 v38, v94, v94
	v_pk_add_f32 v[40:41], v[44:45], v[42:43]
	v_pk_fma_f32 v[42:43], v[94:95], v[94:95], v[38:39] op_sel_hi:[1,1,0]
	v_mul_f32_e32 v38, v96, v96
	v_pk_add_f32 v[40:41], v[40:41], v[40:41] op_sel_hi:[0,1]
	v_pk_fma_f32 v[44:45], v[96:97], v[96:97], v[38:39] op_sel_hi:[1,1,0]
	v_mul_f32_e32 v42, v90, v90
	v_mul_f32_e32 v44, v91, v91
	v_mul_f32_e32 v40, v92, v92
	v_mul_f32_e32 v38, v93, v93
	v_pk_add_f32 v[42:43], v[42:43], v[44:45]
	v_pk_add_f32 v[38:39], v[40:41], v[38:39]
	v_pk_mul_f32 v[34:35], v[34:35], v[130:131] op_sel_hi:[1,0]
	v_pk_add_f32 v[38:39], v[42:43], v[38:39]
	v_pk_mul_f32 v[36:37], v[36:37], v[130:131] op_sel_hi:[1,0]
	v_add_f32_e32 v38, v38, v39
	ds_bpermute_b32 v39, v115, v38
	v_pk_mul_f32 v[36:37], v[30:31], v[36:37]
	v_pk_mul_f32 v[34:35], v[28:29], v[34:35]
	global_store_dwordx4 v[124:125], v[34:37], off offset:3072 nt
	v_lshl_add_u64 v[60:61], v[102:103], 0, s[4:5]
	s_waitcnt lgkmcnt(0)
; __device__ __forceinline__ float rsq_f(float x) { return __builtin_amdgcn_rsqf(x); }
; __device__ __forceinline__ void final_row(const f32x4 (&v)[8], const f32x4 (&g)[8], float* orow, int lane) {
;     float ss = 0.f;
; #pragma unroll
;     for (int j = 0; j < 8; ++j) ss += (v[j].x * v[j].x + v[j].y * v[j].y) + (v[j].z * v[j].z + v[j].w * v[j].w);
;     const float rstd = rsq_f(wave_sum(ss) * (1.f / DM) + EPS);
; #pragma unroll
;     for (int j = 0; j < 8; ++j) ((f32x4*)orow)[lane + 64 * j] = v[j] * rstd * g[j];
; __device__ __forceinline__ void phase_final(const float* x, const float* g, float* out, int gw, int NGW, int lane) {
;     ...
;     for (int j = 0; j < 8; ++j) v[j] = ((const f32x4*)(x + (size_t)row0 * DM))[lane + 64 * j];
; #pragma unroll
;     for (int k = 0; k < 4; ++k) {
;         if (k < 3) {
; #pragma unroll
;             for (int j = 0; j < 8; ++j) w[j] = ((const f32x4*)(x + (size_t)(row0 + k + 1) * DM))[lane + 64 * j];
;         }
;         final_row(v, gg, out + (size_t)(row0 + k) * DM, lane);
; #pragma unroll
;         for (int j = 0; j < 8; ++j) v[j] = w[j];
	v_add_f32_e32 v38, v38, v39
	ds_bpermute_b32 v39, v116, v38
	v_lshl_add_u64 v[34:35], v[112:113], 0, s[6:7]
	v_lshl_add_u64 v[36:37], v[34:35], 0, v[98:99]
	global_load_dwordx4 v[122:125], v[36:37], off offset:1024 nt
	global_load_dwordx4 v[126:129], v[36:37], off nt
	global_load_dwordx4 v[46:49], v[36:37], off offset:3072 nt
	global_load_dwordx4 v[130:133], v[36:37], off offset:2048 nt
	s_waitcnt lgkmcnt(0)
	v_add_f32_e32 v38, v38, v39
	ds_bpermute_b32 v39, v117, v38
	v_lshl_add_u64 v[40:41], v[34:35], 0, v[104:105]
	v_lshl_add_u64 v[54:55], v[34:35], 0, v[106:107]
	v_lshl_add_u64 v[56:57], v[34:35], 0, v[108:109]
	s_waitcnt lgkmcnt(0)
	v_add_f32_e32 v38, v38, v39
	ds_bpermute_b32 v39, v118, v38
	s_waitcnt lgkmcnt(0)
	v_add_f32_e32 v38, v38, v39
	ds_bpermute_b32 v39, v119, v38
	s_waitcnt lgkmcnt(0)
	v_add_f32_e32 v36, v38, v39
	ds_bpermute_b32 v37, v120, v36
	v_lshl_add_u64 v[38:39], v[34:35], 0, v[110:111]
	s_waitcnt lgkmcnt(0)
	v_add_f32_e32 v34, v36, v37
	v_fmamk_f32 v34, v34, 0x3a000000, v114
	v_rsq_f32_e32 v58, v34
	global_load_dwordx4 v[42:45], v[54:55], off nt
	global_load_dwordx4 v[50:53], v[56:57], off nt
	global_load_dwordx4 v[34:37], v[38:39], off nt
	s_nop 0
	global_load_dwordx4 v[38:41], v[40:41], off nt
	v_pk_mul_f32 v[54:55], v[74:75], v[58:59] op_sel_hi:[1,0]
	v_pk_mul_f32 v[56:57], v[76:77], v[58:59] op_sel_hi:[1,0]
	v_pk_mul_f32 v[54:55], v[0:1], v[54:55]
	v_pk_mul_f32 v[56:57], v[2:3], v[56:57]
	global_store_dwordx4 v[60:61], v[54:57], off nt
	s_waitcnt vmcnt(8)
	v_mov_b32_e32 v74, v123
	v_pk_mul_f32 v[54:55], v[66:67], v[58:59] op_sel_hi:[1,0]
	v_pk_mul_f32 v[56:57], v[68:69], v[58:59] op_sel_hi:[1,0]
	v_pk_mul_f32 v[54:55], v[4:5], v[54:55]
	v_pk_mul_f32 v[56:57], v[6:7], v[56:57]
	global_store_dwordx4 v[60:61], v[54:57], off offset:1024 nt
	s_waitcnt vmcnt(8)
	v_mov_b32_e32 v75, v127
	v_pk_mul_f32 v[74:75], v[74:75], v[74:75]
	v_pk_mul_f32 v[54:55], v[78:79], v[58:59] op_sel_hi:[1,0]
	v_pk_mul_f32 v[56:57], v[80:81], v[58:59] op_sel_hi:[1,0]
	v_pk_mul_f32 v[54:55], v[8:9], v[54:55]
	v_pk_mul_f32 v[56:57], v[10:11], v[56:57]
	global_store_dwordx4 v[60:61], v[54:57], off offset:2048 nt
	v_mov_b32_e32 v76, v125
	v_mov_b32_e32 v77, v129
	v_pk_mul_f32 v[54:55], v[70:71], v[58:59] op_sel_hi:[1,0]
	v_pk_mul_f32 v[56:57], v[72:73], v[58:59] op_sel_hi:[1,0]
	v_pk_mul_f32 v[54:55], v[12:13], v[54:55]
	v_pk_mul_f32 v[56:57], v[14:15], v[56:57]
	global_store_dwordx4 v[60:61], v[54:57], off offset:3072 nt
	v_add_co_u32_e32 v60, vcc, s8, v60
	s_nop 0
	v_pk_mul_f32 v[54:55], v[86:87], v[58:59] op_sel_hi:[1,0]
	v_pk_mul_f32 v[56:57], v[88:89], v[58:59] op_sel_hi:[1,0]
	v_pk_mul_f32 v[54:55], v[16:17], v[54:55]
	v_pk_mul_f32 v[56:57], v[18:19], v[56:57]
	v_addc_co_u32_e32 v61, vcc, 0, v61, vcc
	global_store_dwordx4 v[60:61], v[54:57], off nt
	v_lshl_add_u64 v[70:71], v[112:113], 0, s[2:3]
	v_lshl_add_u64 v[72:73], v[70:71], 0, v[98:99]
	v_pk_mul_f32 v[54:55], v[82:83], v[58:59] op_sel_hi:[1,0]
	v_pk_mul_f32 v[56:57], v[84:85], v[58:59] op_sel_hi:[1,0]
	v_pk_mul_f32 v[54:55], v[20:21], v[54:55]
	v_pk_mul_f32 v[56:57], v[22:23], v[56:57]
	global_store_dwordx4 v[60:61], v[54:57], off offset:1024 nt
	v_pk_mul_f32 v[76:77], v[76:77], v[76:77]
	s_nop 0
	v_pk_mul_f32 v[54:55], v[94:95], v[58:59] op_sel_hi:[1,0]
	v_pk_mul_f32 v[56:57], v[96:97], v[58:59] op_sel_hi:[1,0]
	v_pk_mul_f32 v[54:55], v[24:25], v[54:55]
	v_pk_mul_f32 v[56:57], v[26:27], v[56:57]
	global_store_dwordx4 v[60:61], v[54:57], off offset:2048 nt
	s_nop 1
	v_pk_mul_f32 v[54:55], v[90:91], v[58:59] op_sel_hi:[1,0]
	v_pk_mul_f32 v[56:57], v[92:93], v[58:59] op_sel_hi:[1,0]
	v_pk_mul_f32 v[54:55], v[28:29], v[54:55]
	v_pk_mul_f32 v[56:57], v[30:31], v[56:57]
	global_store_dwordx4 v[60:61], v[54:57], off offset:3072 nt
	global_load_dwordx4 v[54:57], v[72:73], off offset:3072 nt
	s_nop 0
	global_load_dwordx4 v[58:61], v[72:73], off offset:2048 nt
	global_load_dwordx4 v[62:65], v[72:73], off offset:1024 nt
	global_load_dwordx4 v[66:69], v[72:73], off nt
	v_mov_b32_e32 v72, v122
	v_mov_b32_e32 v73, v126
	v_pk_fma_f32 v[72:73], v[72:73], v[72:73], v[74:75]
	v_mov_b32_e32 v74, v124
	v_mov_b32_e32 v75, v128
	v_pk_fma_f32 v[74:75], v[74:75], v[74:75], v[76:77]
	s_waitcnt vmcnt(16)
	v_pk_mul_f32 v[76:77], v[130:131], v[130:131]
	v_pk_add_f32 v[72:73], v[72:73], v[74:75]
	v_pk_mul_f32 v[74:75], v[132:133], v[132:133]
	v_pk_add_f32 v[72:73], v[72:73], v[72:73] op_sel_hi:[0,1]
	v_pk_mov_b32 v[78:79], v[76:77], v[74:75] op_sel:[1,0]
	v_mov_b32_e32 v77, v75
	v_mul_f32_e32 v72, v46, v46
	v_pk_add_f32 v[74:75], v[78:79], v[76:77]
	v_pk_fma_f32 v[76:77], v[46:47], v[46:47], v[72:73] op_sel_hi:[1,1,0]
	v_mul_f32_e32 v72, v48, v48
	v_pk_add_f32 v[74:75], v[74:75], v[74:75] op_sel_hi:[0,1]
	v_pk_fma_f32 v[78:79], v[48:49], v[48:49], v[72:73] op_sel_hi:[1,1,0]
	s_waitcnt vmcnt(14)
	v_mul_f32_e32 v76, v50, v50
	v_mul_f32_e32 v78, v51, v51
	v_mul_f32_e32 v74, v52, v52
	v_mul_f32_e32 v72, v53, v53
	v_pk_add_f32 v[76:77], v[76:77], v[78:79]
	v_pk_add_f32 v[72:73], v[74:75], v[72:73]
	v_pk_mul_f32 v[74:75], v[44:45], v[44:45]
	v_pk_add_f32 v[72:73], v[76:77], v[72:73]
	v_pk_mul_f32 v[76:77], v[42:43], v[42:43]
	v_pk_add_f32 v[72:73], v[72:73], v[72:73] op_sel_hi:[0,1]
	v_pk_mov_b32 v[78:79], v[76:77], v[74:75] op_sel:[1,0]
	v_mov_b32_e32 v77, v75
	s_waitcnt vmcnt(12)
	v_mul_f32_e32 v72, v38, v38
	v_pk_add_f32 v[74:75], v[78:79], v[76:77]
	v_pk_fma_f32 v[76:77], v[38:39], v[38:39], v[72:73] op_sel_hi:[1,1,0]
	v_mul_f32_e32 v72, v40, v40
	v_pk_add_f32 v[74:75], v[74:75], v[74:75] op_sel_hi:[0,1]
	v_pk_fma_f32 v[78:79], v[40:41], v[40:41], v[72:73] op_sel_hi:[1,1,0]
	v_mul_f32_e32 v76, v34, v34
	v_mul_f32_e32 v78, v35, v35
	v_mul_f32_e32 v74, v36, v36
	v_mul_f32_e32 v72, v37, v37
	v_pk_add_f32 v[76:77], v[76:77], v[78:79]
	v_pk_add_f32 v[72:73], v[74:75], v[72:73]
	v_lshl_add_u64 v[92:93], v[102:103], 0, s[6:7]
	v_pk_add_f32 v[72:73], v[76:77], v[72:73]
	s_waitcnt vmcnt(1)
; __device__ __forceinline__ float rsq_f(float x) { return __builtin_amdgcn_rsqf(x); }
; __device__ __forceinline__ void final_row(const f32x4 (&v)[8], const f32x4 (&g)[8], float* orow, int lane) {
;     float ss = 0.f;
; #pragma unroll
;     for (int j = 0; j < 8; ++j) ss += (v[j].x * v[j].x + v[j].y * v[j].y) + (v[j].z * v[j].z + v[j].w * v[j].w);
;     const float rstd = rsq_f(wave_sum(ss) * (1.f / DM) + EPS);
; #pragma unroll
;     for (int j = 0; j < 8; ++j) ((f32x4*)orow)[lane + 64 * j] = v[j] * rstd * g[j];
; __device__ __forceinline__ void phase_final(const float* x, const float* g, float* out, int gw, int NGW, int lane) {
;     ...
;     for (int j = 0; j < 8; ++j) v[j] = ((const f32x4*)(x + (size_t)row0 * DM))[lane + 64 * j];
; #pragma unroll
;     for (int k = 0; k < 4; ++k) {
;         if (k < 3) {
; #pragma unroll
;             for (int j = 0; j < 8; ++j) w[j] = ((const f32x4*)(x + (size_t)(row0 + k + 1) * DM))[lane + 64 * j];
;         }
;         final_row(v, gg, out + (size_t)(row0 + k) * DM, lane);
; #pragma unroll
;         for (int j = 0; j < 8; ++j) v[j] = w[j];
	v_mov_b32_e32 v94, v65
	v_add_f32_e32 v74, v72, v73
	ds_bpermute_b32 v75, v115, v74
	v_lshl_add_u64 v[72:73], v[70:71], 0, v[108:109]
	global_load_dwordx4 v[82:85], v[72:73], off nt
	v_lshl_add_u64 v[72:73], v[70:71], 0, v[106:107]
	global_load_dwordx4 v[78:81], v[72:73], off nt
	s_waitcnt lgkmcnt(0)
	v_add_f32_e32 v74, v74, v75
	ds_bpermute_b32 v75, v116, v74
	v_lshl_add_u64 v[72:73], v[70:71], 0, v[104:105]
	v_lshl_add_u64 v[70:71], v[70:71], 0, v[110:111]
	s_waitcnt vmcnt(2)
	v_mov_b32_e32 v95, v69
	v_pk_mul_f32 v[94:95], v[94:95], v[94:95]
	s_waitcnt lgkmcnt(0)
	v_add_f32_e32 v86, v74, v75
	global_load_dwordx4 v[74:77], v[72:73], off nt
	ds_bpermute_b32 v87, v117, v86
	global_load_dwordx4 v[70:73], v[70:71], off nt
	s_waitcnt lgkmcnt(0)
	v_add_f32_e32 v86, v86, v87
	ds_bpermute_b32 v87, v118, v86
	s_waitcnt lgkmcnt(0)
	v_add_f32_e32 v86, v86, v87
	ds_bpermute_b32 v87, v119, v86
	s_waitcnt lgkmcnt(0)
	v_add_f32_e32 v86, v86, v87
	ds_bpermute_b32 v87, v120, v86
	s_waitcnt lgkmcnt(0)
	v_add_f32_e32 v86, v86, v87
	v_fmamk_f32 v86, v86, 0x3a000000, v114
	v_rsq_f32_e32 v90, v86
	s_nop 0
	v_pk_mul_f32 v[86:87], v[126:127], v[90:91] op_sel_hi:[1,0]
	v_pk_mul_f32 v[88:89], v[128:129], v[90:91] op_sel_hi:[1,0]
	v_pk_mul_f32 v[86:87], v[0:1], v[86:87]
	v_pk_mul_f32 v[88:89], v[2:3], v[88:89]
	global_store_dwordx4 v[92:93], v[86:89], off nt
	v_pk_mul_f32 v[46:47], v[46:47], v[90:91] op_sel_hi:[1,0]
	v_pk_mul_f32 v[48:49], v[48:49], v[90:91] op_sel_hi:[1,0]
	v_pk_mul_f32 v[86:87], v[122:123], v[90:91] op_sel_hi:[1,0]
	v_pk_mul_f32 v[88:89], v[124:125], v[90:91] op_sel_hi:[1,0]
	v_pk_mul_f32 v[86:87], v[4:5], v[86:87]
	v_pk_mul_f32 v[88:89], v[6:7], v[88:89]
	global_store_dwordx4 v[92:93], v[86:89], off offset:1024 nt
	v_pk_mul_f32 v[48:49], v[14:15], v[48:49]
	v_pk_mul_f32 v[46:47], v[12:13], v[46:47]
	v_pk_mul_f32 v[86:87], v[130:131], v[90:91] op_sel_hi:[1,0]
	v_pk_mul_f32 v[88:89], v[132:133], v[90:91] op_sel_hi:[1,0]
	v_pk_mul_f32 v[86:87], v[8:9], v[86:87]
	v_pk_mul_f32 v[88:89], v[10:11], v[88:89]
	global_store_dwordx4 v[92:93], v[86:89], off offset:2048 nt
	global_store_dwordx4 v[92:93], v[46:49], off offset:3072 nt
	v_pk_mul_f32 v[42:43], v[42:43], v[90:91] op_sel_hi:[1,0]
	v_mov_b32_e32 v88, v63
	v_mov_b32_e32 v89, v67
	v_mov_b32_e32 v86, v62
	v_mov_b32_e32 v87, v66
	v_pk_mul_f32 v[88:89], v[88:89], v[88:89]
	v_pk_mul_f32 v[48:49], v[52:53], v[90:91] op_sel_hi:[1,0]
	v_pk_fma_f32 v[86:87], v[86:87], v[86:87], v[88:89]
	v_mov_b32_e32 v88, v64
	v_mov_b32_e32 v89, v68
	v_pk_fma_f32 v[88:89], v[88:89], v[88:89], v[94:95]
	v_pk_mul_f32 v[94:95], v[58:59], v[58:59]
	v_pk_add_f32 v[86:87], v[86:87], v[88:89]
	v_pk_mul_f32 v[88:89], v[60:61], v[60:61]
	v_pk_add_f32 v[86:87], v[86:87], v[86:87] op_sel_hi:[0,1]
	v_pk_mov_b32 v[96:97], v[94:95], v[88:89] op_sel:[1,0]
	v_mov_b32_e32 v95, v89
	v_mul_f32_e32 v86, v54, v54
	v_pk_add_f32 v[88:89], v[96:97], v[94:95]
	v_pk_fma_f32 v[94:95], v[54:55], v[54:55], v[86:87] op_sel_hi:[1,1,0]
	v_mul_f32_e32 v86, v56, v56
	v_pk_add_f32 v[88:89], v[88:89], v[88:89] op_sel_hi:[0,1]
	v_pk_fma_f32 v[96:97], v[56:57], v[56:57], v[86:87] op_sel_hi:[1,1,0]
	s_waitcnt vmcnt(7)
	v_mul_f32_e32 v94, v82, v82
	v_mul_f32_e32 v96, v83, v83
	v_mul_f32_e32 v88, v84, v84
	v_mul_f32_e32 v86, v85, v85
	v_pk_add_f32 v[94:95], v[94:95], v[96:97]
	v_pk_add_f32 v[86:87], v[88:89], v[86:87]
	s_waitcnt vmcnt(6)
	v_pk_mul_f32 v[88:89], v[80:81], v[80:81]
	v_pk_add_f32 v[86:87], v[94:95], v[86:87]
	v_pk_mul_f32 v[94:95], v[78:79], v[78:79]
	v_pk_add_f32 v[86:87], v[86:87], v[86:87] op_sel_hi:[0,1]
	v_pk_mov_b32 v[96:97], v[94:95], v[88:89] op_sel:[1,0]
	v_mov_b32_e32 v95, v89
	s_waitcnt vmcnt(5)
	v_mul_f32_e32 v86, v74, v74
	v_pk_add_f32 v[88:89], v[96:97], v[94:95]
	v_pk_fma_f32 v[94:95], v[74:75], v[74:75], v[86:87] op_sel_hi:[1,1,0]
	v_mul_f32_e32 v86, v76, v76
	v_pk_add_f32 v[88:89], v[88:89], v[88:89] op_sel_hi:[0,1]
	v_pk_fma_f32 v[96:97], v[76:77], v[76:77], v[86:87] op_sel_hi:[1,1,0]
	s_waitcnt vmcnt(4)
	v_mul_f32_e32 v94, v70, v70
	v_mul_f32_e32 v96, v71, v71
	v_mul_f32_e32 v88, v72, v72
	v_mul_f32_e32 v86, v73, v73
	v_pk_add_f32 v[94:95], v[94:95], v[96:97]
	v_pk_add_f32 v[86:87], v[88:89], v[86:87]
	v_pk_mul_f32 v[46:47], v[50:51], v[90:91] op_sel_hi:[1,0]
	v_pk_add_f32 v[86:87], v[94:95], v[86:87]
	v_add_co_u32_e32 v50, vcc, s8, v92
	v_add_f32_e32 v86, v86, v87
	ds_bpermute_b32 v87, v115, v86
	v_pk_mul_f32 v[48:49], v[18:19], v[48:49]
	v_pk_mul_f32 v[46:47], v[16:17], v[46:47]
	v_addc_co_u32_e32 v51, vcc, 0, v93, vcc
	s_waitcnt lgkmcnt(0)
	v_add_f32_e32 v86, v86, v87
	ds_bpermute_b32 v87, v116, v86
	global_store_dwordx4 v[50:51], v[46:49], off nt
	v_pk_mul_f32 v[44:45], v[44:45], v[90:91] op_sel_hi:[1,0]
	v_pk_mul_f32 v[42:43], v[20:21], v[42:43]
	v_pk_mul_f32 v[44:45], v[22:23], v[44:45]
	s_waitcnt lgkmcnt(0)
	v_add_f32_e32 v52, v86, v87
	ds_bpermute_b32 v53, v117, v52
	global_store_dwordx4 v[50:51], v[42:45], off offset:1024 nt
	v_pk_mul_f32 v[38:39], v[38:39], v[90:91] op_sel_hi:[1,0]
	v_pk_mul_f32 v[40:41], v[40:41], v[90:91] op_sel_hi:[1,0]
	v_pk_mul_f32 v[38:39], v[24:25], v[38:39]
	s_waitcnt lgkmcnt(0)
	v_add_f32_e32 v46, v52, v53
	ds_bpermute_b32 v47, v118, v46
	v_pk_mul_f32 v[40:41], v[26:27], v[40:41]
	global_store_dwordx4 v[50:51], v[38:41], off offset:2048 nt
	v_pk_mul_f32 v[34:35], v[34:35], v[90:91] op_sel_hi:[1,0]
	v_pk_mul_f32 v[36:37], v[36:37], v[90:91] op_sel_hi:[1,0]
	s_waitcnt lgkmcnt(0)
	v_add_f32_e32 v46, v46, v47
	ds_bpermute_b32 v47, v119, v46
	v_pk_mul_f32 v[36:37], v[30:31], v[36:37]
	v_pk_mul_f32 v[34:35], v[28:29], v[34:35]
	global_store_dwordx4 v[50:51], v[34:37], off offset:3072 nt
	v_lshl_add_u64 v[40:41], v[102:103], 0, s[2:3]
	s_waitcnt lgkmcnt(0)
; __device__ __forceinline__ float rsq_f(float x) { return __builtin_amdgcn_rsqf(x); }
; __device__ __forceinline__ void final_row(const f32x4 (&v)[8], const f32x4 (&g)[8], float* orow, int lane) {
;     float ss = 0.f;
; #pragma unroll
;     for (int j = 0; j < 8; ++j) ss += (v[j].x * v[j].x + v[j].y * v[j].y) + (v[j].z * v[j].z + v[j].w * v[j].w);
;     const float rstd = rsq_f(wave_sum(ss) * (1.f / DM) + EPS);
; #pragma unroll
;     for (int j = 0; j < 8; ++j) ((f32x4*)orow)[lane + 64 * j] = v[j] * rstd * g[j];
; __device__ __forceinline__ void phase_final(const float* x, const float* g, float* out, int gw, int NGW, int lane) {
;     ...
;     for (int row = MP + gw; row < MT; row += NGW) {
; #pragma unroll
;         for (int j = 0; j < 8; ++j) v[j] = ((const f32x4*)(x + (size_t)row * DM))[lane + 64 * j];
;         final_row(v, gg, out + (size_t)row * DM, lane);
	v_add_f32_e32 v42, v46, v47
	ds_bpermute_b32 v43, v120, v42
	s_waitcnt lgkmcnt(0)
	v_add_f32_e32 v38, v42, v43
	v_fmamk_f32 v38, v38, 0x3a000000, v114
	v_rsq_f32_e32 v38, v38
	s_nop 0
	v_pk_mul_f32 v[34:35], v[66:67], v[38:39] op_sel_hi:[1,0]
	v_pk_mul_f32 v[36:37], v[68:69], v[38:39] op_sel_hi:[1,0]
	v_pk_mul_f32 v[34:35], v[0:1], v[34:35]
	v_pk_mul_f32 v[36:37], v[2:3], v[36:37]
	global_store_dwordx4 v[40:41], v[34:37], off nt
	s_nop 1
	v_pk_mul_f32 v[34:35], v[62:63], v[38:39] op_sel_hi:[1,0]
	v_pk_mul_f32 v[36:37], v[64:65], v[38:39] op_sel_hi:[1,0]
	v_pk_mul_f32 v[34:35], v[4:5], v[34:35]
	v_pk_mul_f32 v[36:37], v[6:7], v[36:37]
	global_store_dwordx4 v[40:41], v[34:37], off offset:1024 nt
	s_nop 1
	v_pk_mul_f32 v[34:35], v[58:59], v[38:39] op_sel_hi:[1,0]
	v_pk_mul_f32 v[36:37], v[60:61], v[38:39] op_sel_hi:[1,0]
	v_pk_mul_f32 v[34:35], v[8:9], v[34:35]
	v_pk_mul_f32 v[36:37], v[10:11], v[36:37]
	global_store_dwordx4 v[40:41], v[34:37], off offset:2048 nt
	s_nop 1
	v_pk_mul_f32 v[34:35], v[54:55], v[38:39] op_sel_hi:[1,0]
	v_pk_mul_f32 v[36:37], v[56:57], v[38:39] op_sel_hi:[1,0]
	v_pk_mul_f32 v[34:35], v[12:13], v[34:35]
	v_pk_mul_f32 v[36:37], v[14:15], v[36:37]
	global_store_dwordx4 v[40:41], v[34:37], off offset:3072 nt
	v_add_co_u32_e32 v40, vcc, s8, v40
	s_nop 0
	v_pk_mul_f32 v[34:35], v[82:83], v[38:39] op_sel_hi:[1,0]
	v_pk_mul_f32 v[36:37], v[84:85], v[38:39] op_sel_hi:[1,0]
	v_pk_mul_f32 v[34:35], v[16:17], v[34:35]
	v_pk_mul_f32 v[36:37], v[18:19], v[36:37]
	v_addc_co_u32_e32 v41, vcc, 0, v41, vcc
	global_store_dwordx4 v[40:41], v[34:37], off nt
	s_nop 1
	v_pk_mul_f32 v[34:35], v[78:79], v[38:39] op_sel_hi:[1,0]
	v_pk_mul_f32 v[36:37], v[80:81], v[38:39] op_sel_hi:[1,0]
	v_pk_mul_f32 v[34:35], v[20:21], v[34:35]
	v_pk_mul_f32 v[36:37], v[22:23], v[36:37]
	global_store_dwordx4 v[40:41], v[34:37], off offset:1024 nt
	s_nop 1
	v_pk_mul_f32 v[34:35], v[74:75], v[38:39] op_sel_hi:[1,0]
	v_pk_mul_f32 v[36:37], v[76:77], v[38:39] op_sel_hi:[1,0]
	v_pk_mul_f32 v[34:35], v[24:25], v[34:35]
	v_pk_mul_f32 v[36:37], v[26:27], v[36:37]
	global_store_dwordx4 v[40:41], v[34:37], off offset:2048 nt
	s_nop 1
	v_pk_mul_f32 v[34:35], v[70:71], v[38:39] op_sel_hi:[1,0]
	v_pk_mul_f32 v[36:37], v[72:73], v[38:39] op_sel_hi:[1,0]
	v_pk_mul_f32 v[34:35], v[28:29], v[34:35]
	v_pk_mul_f32 v[36:37], v[30:31], v[36:37]
	global_store_dwordx4 v[40:41], v[34:37], off offset:3072 nt
	s_cbranch_scc1 .LBB0_706
	s_ashr_i32 s1, s0, 31
	s_add_i32 s4, s0, 0x1800
	s_lshl_b64 s[0:1], s[0:1], 13
	s_add_u32 s0, s0, 0x4000000
	s_addc_u32 s1, s1, 0
	v_lshl_add_u64 v[34:35], v[100:101], 0, s[0:1]
	v_lshl_add_u64 v[32:33], v[32:33], 0, s[0:1]
	s_mov_b64 s[2:3], 0x1000000
; __device__ __forceinline__ float rsq_f(float x) { return __builtin_amdgcn_rsqf(x); }
; __device__ __forceinline__ void final_row(const f32x4 (&v)[8], const f32x4 (&g)[8], float* orow, int lane) {
;     float ss = 0.f;
; #pragma unroll
;     for (int j = 0; j < 8; ++j) ss += (v[j].x * v[j].x + v[j].y * v[j].y) + (v[j].z * v[j].z + v[j].w * v[j].w);
;     const float rstd = rsq_f(wave_sum(ss) * (1.f / DM) + EPS);
; #pragma unroll
;     for (int j = 0; j < 8; ++j) ((f32x4*)orow)[lane + 64 * j] = v[j] * rstd * g[j];
; __device__ __forceinline__ void phase_final(const float* x, const float* g, float* out, int gw, int NGW, int lane) {
;     ...
;     for (int row = MP + gw; row < MT; row += NGW) {
; #pragma unroll
;         for (int j = 0; j < 8; ++j) v[j] = ((const f32x4*)(x + (size_t)row * DM))[lane + 64 * j];
;         final_row(v, gg, out + (size_t)row * DM, lane);
;     }
.LBB0_705:
	v_lshl_add_u64 v[52:53], v[34:35], 0, v[98:99]
	v_add_co_u32_e32 v54, vcc, 0x1c200000, v52
	v_lshl_add_u64 v[68:69], v[32:33], 0, v[98:99]
	s_nop 0
	v_addc_co_u32_e32 v55, vcc, 0, v53, vcc
	global_load_dwordx4 v[36:39], v[54:55], off nt
	global_load_dwordx4 v[40:43], v[54:55], off offset:1024 nt
	global_load_dwordx4 v[44:47], v[54:55], off offset:2048 nt
	global_load_dwordx4 v[48:51], v[54:55], off offset:3072 nt
	v_add_co_u32_e32 v72, vcc, 0x1c201000, v52
	s_addk_i32 s4, 0x800
	s_nop 0
	v_addc_co_u32_e32 v73, vcc, 0, v53, vcc
	global_load_dwordx4 v[52:55], v[72:73], off offset:1024 nt
	global_load_dwordx4 v[56:59], v[72:73], off offset:2048 nt
	global_load_dwordx4 v[60:63], v[72:73], off nt
	global_load_dwordx4 v[64:67], v[72:73], off offset:3072 nt
	v_lshl_add_u64 v[34:35], v[34:35], 0, s[2:3]
	v_lshl_add_u64 v[32:33], v[32:33], 0, s[2:3]
	v_add_co_u32_e64 v70, s[0:1], s8, v68
	s_cmpk_lt_i32 s4, 0x1880
	s_nop 0
	v_addc_co_u32_e64 v71, s[0:1], 0, v69, s[0:1]
	s_waitcnt vmcnt(7)
	v_mov_b32_e32 v74, v37
	s_waitcnt vmcnt(6)
	v_mov_b32_e32 v75, v41
	v_mov_b32_e32 v78, v39
	v_mov_b32_e32 v79, v43
	v_mov_b32_e32 v72, v36
	v_mov_b32_e32 v73, v40
	v_mov_b32_e32 v76, v38
	v_mov_b32_e32 v77, v42
	s_waitcnt vmcnt(5)
	v_pk_mul_f32 v[80:81], v[46:47], v[46:47]
	v_pk_mul_f32 v[82:83], v[44:45], v[44:45]
	v_pk_mul_f32 v[74:75], v[74:75], v[74:75]
	v_pk_mul_f32 v[78:79], v[78:79], v[78:79]
	v_pk_mov_b32 v[88:89], v[82:83], v[80:81] op_sel:[1,0]
	v_mov_b32_e32 v83, v81
	v_pk_fma_f32 v[72:73], v[72:73], v[72:73], v[74:75]
	v_pk_fma_f32 v[74:75], v[76:77], v[76:77], v[78:79]
	s_waitcnt vmcnt(4)
	v_mul_f32_e32 v84, v48, v48
	v_mul_f32_e32 v86, v50, v50
	v_pk_add_f32 v[76:77], v[88:89], v[82:83]
	v_pk_add_f32 v[72:73], v[72:73], v[74:75]
	v_pk_fma_f32 v[80:81], v[48:49], v[48:49], v[84:85] op_sel_hi:[1,1,0]
	v_pk_fma_f32 v[84:85], v[50:51], v[50:51], v[86:87] op_sel_hi:[1,1,0]
	v_pk_add_f32 v[74:75], v[76:77], v[76:77] op_sel_hi:[0,1]
	v_pk_add_f32 v[72:73], v[72:73], v[72:73] op_sel_hi:[0,1]
	s_waitcnt vmcnt(3)
	v_pk_mul_f32 v[86:87], v[54:55], v[54:55]
	v_pk_mul_f32 v[90:91], v[52:53], v[52:53]
	s_waitcnt vmcnt(1)
	v_mul_f32_e32 v80, v60, v60
	v_mul_f32_e32 v84, v61, v61
	v_mul_f32_e32 v74, v62, v62
	v_mul_f32_e32 v72, v63, v63
	v_pk_mov_b32 v[78:79], v[90:91], v[86:87] op_sel:[1,0]
	v_mov_b32_e32 v91, v87
	v_pk_add_f32 v[76:77], v[80:81], v[84:85]
	v_pk_add_f32 v[72:73], v[74:75], v[72:73]
	v_mul_f32_e32 v92, v56, v56
	v_mul_f32_e32 v94, v58, v58
	v_pk_add_f32 v[78:79], v[78:79], v[90:91]
	v_pk_add_f32 v[72:73], v[76:77], v[72:73]
	v_pk_fma_f32 v[82:83], v[56:57], v[56:57], v[92:93] op_sel_hi:[1,1,0]
	v_pk_fma_f32 v[86:87], v[58:59], v[58:59], v[94:95] op_sel_hi:[1,1,0]
	v_pk_add_f32 v[78:79], v[78:79], v[78:79] op_sel_hi:[0,1]
	v_pk_add_f32 v[72:73], v[72:73], v[72:73] op_sel_hi:[0,1]
	s_waitcnt vmcnt(0)
	v_mul_f32_e32 v82, v64, v64
	v_mul_f32_e32 v86, v65, v65
	v_mul_f32_e32 v78, v66, v66
	v_mul_f32_e32 v72, v67, v67
	v_pk_add_f32 v[80:81], v[82:83], v[86:87]
	v_pk_add_f32 v[72:73], v[78:79], v[72:73]
	s_nop 0
	v_pk_add_f32 v[72:73], v[80:81], v[72:73]
	s_nop 0
	v_add_f32_e32 v72, v72, v73
	ds_bpermute_b32 v73, v115, v72
	s_waitcnt lgkmcnt(0)
	v_add_f32_e32 v72, v72, v73
	ds_bpermute_b32 v73, v116, v72
	s_waitcnt lgkmcnt(0)
	v_add_f32_e32 v72, v72, v73
	ds_bpermute_b32 v73, v117, v72
	s_waitcnt lgkmcnt(0)
	v_add_f32_e32 v72, v72, v73
	ds_bpermute_b32 v73, v118, v72
	s_waitcnt lgkmcnt(0)
	v_add_f32_e32 v72, v72, v73
	ds_bpermute_b32 v73, v119, v72
	s_waitcnt lgkmcnt(0)
	v_add_f32_e32 v72, v72, v73
	ds_bpermute_b32 v73, v120, v72
	s_waitcnt lgkmcnt(0)
	v_add_f32_e32 v72, v72, v73
	v_fmamk_f32 v72, v72, 0x3a000000, v114
	v_rsq_f32_e32 v72, v72
	s_nop 0
	v_pk_mul_f32 v[36:37], v[36:37], v[72:73] op_sel_hi:[1,0]
	v_pk_mul_f32 v[38:39], v[38:39], v[72:73] op_sel_hi:[1,0]
	v_pk_mul_f32 v[40:41], v[40:41], v[72:73] op_sel_hi:[1,0]
	v_pk_mul_f32 v[42:43], v[42:43], v[72:73] op_sel_hi:[1,0]
	v_pk_mul_f32 v[44:45], v[44:45], v[72:73] op_sel_hi:[1,0]
	v_pk_mul_f32 v[46:47], v[46:47], v[72:73] op_sel_hi:[1,0]
	v_pk_mul_f32 v[48:49], v[48:49], v[72:73] op_sel_hi:[1,0]
	v_pk_mul_f32 v[50:51], v[50:51], v[72:73] op_sel_hi:[1,0]
	v_pk_mul_f32 v[60:61], v[60:61], v[72:73] op_sel_hi:[1,0]
	v_pk_mul_f32 v[62:63], v[62:63], v[72:73] op_sel_hi:[1,0]
	v_pk_mul_f32 v[74:75], v[52:53], v[72:73] op_sel_hi:[1,0]
	v_pk_mul_f32 v[76:77], v[54:55], v[72:73] op_sel_hi:[1,0]
	v_pk_mul_f32 v[78:79], v[56:57], v[72:73] op_sel_hi:[1,0]
	v_pk_mul_f32 v[80:81], v[58:59], v[72:73] op_sel_hi:[1,0]
	v_pk_mul_f32 v[64:65], v[64:65], v[72:73] op_sel_hi:[1,0]
	v_pk_mul_f32 v[66:67], v[66:67], v[72:73] op_sel_hi:[1,0]
	v_pk_mul_f32 v[38:39], v[2:3], v[38:39]
	v_pk_mul_f32 v[36:37], v[0:1], v[36:37]
	v_pk_mul_f32 v[42:43], v[6:7], v[42:43]
	v_pk_mul_f32 v[40:41], v[4:5], v[40:41]
	v_pk_mul_f32 v[46:47], v[10:11], v[46:47]
	v_pk_mul_f32 v[44:45], v[8:9], v[44:45]
	v_pk_mul_f32 v[50:51], v[14:15], v[50:51]
	v_pk_mul_f32 v[48:49], v[12:13], v[48:49]
	v_pk_mul_f32 v[54:55], v[18:19], v[62:63]
	v_pk_mul_f32 v[52:53], v[16:17], v[60:61]
	v_pk_mul_f32 v[58:59], v[22:23], v[76:77]
	v_pk_mul_f32 v[56:57], v[20:21], v[74:75]
	v_pk_mul_f32 v[62:63], v[26:27], v[80:81]
	v_pk_mul_f32 v[60:61], v[24:25], v[78:79]
	v_pk_mul_f32 v[66:67], v[30:31], v[66:67]
	v_pk_mul_f32 v[64:65], v[28:29], v[64:65]
	global_store_dwordx4 v[68:69], v[36:39], off nt
	global_store_dwordx4 v[68:69], v[40:43], off offset:1024 nt
	global_store_dwordx4 v[68:69], v[44:47], off offset:2048 nt
	global_store_dwordx4 v[68:69], v[48:51], off offset:3072 nt
	global_store_dwordx4 v[70:71], v[52:55], off nt
	global_store_dwordx4 v[70:71], v[56:59], off offset:1024 nt
	global_store_dwordx4 v[70:71], v[60:63], off offset:2048 nt
	global_store_dwordx4 v[70:71], v[64:67], off offset:3072 nt
	s_cbranch_scc1 .LBB0_705
